# v81 + the five K-loop heads placed at byte offset 32 mod 64
# speedup vs baseline: 1.0012x; 1.0012x over previous
.LBB0_266:
	s_xor_b64 s[2:3], s[2:3], -1
	s_mov_b32 s34, s74
	s_add_i32 s74, s74, 1
	s_cmp_lt_u32 s34, 5
	s_mov_b64 s[4:5], s[10:11]
	s_mov_b32 s10, s75
	s_cselect_b64 s[14:15], -1, 0
	s_add_i32 s75, s74, s16
	s_mov_b64 s[12:13], s[8:9]
	s_and_b64 s[8:9], s[14:15], exec
	s_cselect_b32 s8, s75, s10
	s_cselect_b32 s10, s6, s6
	s_ashr_i32 s11, s10, 31
	s_lshl_b64 s[10:11], s[10:11], 19
	s_add_u32 s10, s80, s10
	s_addc_u32 s11, s81, s11
	s_and_b64 s[44:45], s[14:15], exec
	s_cselect_b32 s44, s11, s5
	s_cselect_b32 s45, s10, s4
	s_ashr_i32 s9, s8, 31
	s_lshl_b64 s[8:9], s[8:9], 19
	v_readlane_b32 s47, v255, 14
	s_add_u32 s8, s47, s8
	v_readlane_b32 s47, v255, 15
	s_addc_u32 s9, s47, s9
	s_and_b64 s[14:15], s[14:15], exec
	s_cselect_b32 s47, s9, s13
	s_cselect_b32 s55, s8, s12
	s_add_u32 s4, s4, 0x40080
	s_addc_u32 s5, s5, 0
	s_add_u32 s78, s12, 0x100
	s_addc_u32 s79, s13, 0
	s_mov_b32 s85, -2
	s_waitcnt lgkmcnt(0)
	s_add_i32 s86, 0, 0x10000
	v_add_u32_e32 v0, s86, v150
	v_add_u32_e32 v189, 0x10000, v150
	ds_read_b128 v[142:145], v0
	ds_read_b128 v[146:149], v0 offset:1024
	ds_read_b128 v[152:155], v0 offset:2048
	ds_read_b128 v[156:159], v0 offset:3072
	s_add_u32 s12, s4, 0xfffc0080
	s_addc_u32 s13, s5, -1
	s_cmp_eq_u32 s85, 12
	s_cselect_b32 s15, s44, s13
	s_cselect_b32 s14, s45, s12
	s_cselect_b32 s13, s47, s79
	s_cselect_b32 s12, s55, s78
	s_add_i32 m0, s7, 0xc000
	ds_read_b128 v[160:163], v151
	ds_read_b128 v[164:167], v151 offset:1024
	ds_read_b128 v[168:171], v151 offset:2048
	ds_read_b128 v[172:175], v151 offset:3072
	ds_read_b128 v[176:179], v151 offset:4096
	ds_read_b128 v[180:183], v151 offset:5120
	ds_read_b128 v[184:187], v151 offset:6144
	global_load_lds_dwordx4 v138, s[4:5]
	s_add_i32 m0, s7, 0xe000
	ds_read_b128 v[190:193], v151 offset:7168
	global_load_lds_dwordx4 v140, s[4:5]
	s_waitcnt lgkmcnt(8)
	s_barrier
	s_waitcnt lgkmcnt(0)
	v_mfma_f32_16x16x32_bf16 v[126:129], v[142:145], v[160:163], 0
	v_mfma_f32_16x16x32_bf16 v[122:125], v[152:155], v[160:163], 0
	v_mfma_f32_16x16x32_bf16 v[110:113], v[142:145], v[168:171], 0
	v_mfma_f32_16x16x32_bf16 v[106:109], v[152:155], v[168:171], 0
	v_mfma_f32_16x16x32_bf16 v[94:97], v[142:145], v[176:179], 0
	v_mfma_f32_16x16x32_bf16 v[90:93], v[152:155], v[176:179], 0
	v_mfma_f32_16x16x32_bf16 v[78:81], v[142:145], v[184:187], 0
	v_mfma_f32_16x16x32_bf16 v[74:77], v[152:155], v[184:187], 0
	v_mfma_f32_16x16x32_bf16 v[126:129], v[146:149], v[164:167], v[126:129]
	v_mfma_f32_16x16x32_bf16 v[122:125], v[156:159], v[164:167], v[122:125]
	v_mfma_f32_16x16x32_bf16 v[110:113], v[146:149], v[172:175], v[110:113]
	v_mfma_f32_16x16x32_bf16 v[106:109], v[156:159], v[172:175], v[106:109]
	v_mfma_f32_16x16x32_bf16 v[94:97], v[146:149], v[180:183], v[94:97]
	v_mfma_f32_16x16x32_bf16 v[90:93], v[156:159], v[180:183], v[90:93]
	v_mfma_f32_16x16x32_bf16 v[78:81], v[146:149], v[190:193], v[78:81]
	v_mfma_f32_16x16x32_bf16 v[74:77], v[156:159], v[190:193], v[74:77]
	s_barrier
	s_add_i32 m0, s22, 0x10000
	ds_read_b128 v[194:197], v189 offset:16384
	ds_read_b128 v[198:201], v189 offset:17408
	ds_read_b128 v[202:205], v189 offset:18432
	global_load_lds_dwordx4 v134, s[12:13]
	s_add_i32 m0, s22, 0x12000
	ds_read_b128 v[206:209], v189 offset:19456
	global_load_lds_dwordx4 v130, s[12:13]
	s_barrier
	s_waitcnt lgkmcnt(0)
	v_mfma_f32_16x16x32_bf16 v[118:121], v[194:197], v[160:163], 0
	v_mfma_f32_16x16x32_bf16 v[114:117], v[202:205], v[160:163], 0
	v_mfma_f32_16x16x32_bf16 v[102:105], v[194:197], v[168:171], 0
	v_mfma_f32_16x16x32_bf16 v[98:101], v[202:205], v[168:171], 0
	v_mfma_f32_16x16x32_bf16 v[86:89], v[194:197], v[176:179], 0
	v_mfma_f32_16x16x32_bf16 v[82:85], v[202:205], v[176:179], 0
	v_mfma_f32_16x16x32_bf16 v[70:73], v[194:197], v[184:187], 0
	v_mfma_f32_16x16x32_bf16 v[66:69], v[202:205], v[184:187], 0
	v_mfma_f32_16x16x32_bf16 v[118:121], v[198:201], v[164:167], v[118:121]
	v_mfma_f32_16x16x32_bf16 v[114:117], v[206:209], v[164:167], v[114:117]
	v_mfma_f32_16x16x32_bf16 v[102:105], v[198:201], v[172:175], v[102:105]
	v_mfma_f32_16x16x32_bf16 v[98:101], v[206:209], v[172:175], v[98:101]
	v_mfma_f32_16x16x32_bf16 v[86:89], v[198:201], v[180:183], v[86:89]
	v_mfma_f32_16x16x32_bf16 v[82:85], v[206:209], v[180:183], v[82:85]
	v_mfma_f32_16x16x32_bf16 v[70:73], v[198:201], v[190:193], v[70:73]
	v_mfma_f32_16x16x32_bf16 v[66:69], v[206:209], v[190:193], v[66:69]
	s_mov_b32 m0, s7
	s_mov_b64 s[100:101], s[14:15]
	s_barrier
	ds_read_b128 v[160:163], v151 offset:16384
	ds_read_b128 v[164:167], v151 offset:17408
	ds_read_b128 v[168:171], v151 offset:18432
	ds_read_b128 v[172:175], v151 offset:19456
	ds_read_b128 v[176:179], v151 offset:20480
	ds_read_b128 v[180:183], v151 offset:21504
	ds_read_b128 v[184:187], v151 offset:22528
	global_load_lds_dwordx4 v136, s[100:101]
	s_mov_b32 m0, s23
	ds_read_b128 v[190:193], v151 offset:23552
	global_load_lds_dwordx4 v132, s[100:101]
	s_waitcnt vmcnt(10)
	s_barrier
	s_waitcnt lgkmcnt(0)
	v_mfma_f32_16x16x32_bf16 v[62:65], v[142:145], v[160:163], 0
	v_mfma_f32_16x16x32_bf16 v[58:61], v[152:155], v[160:163], 0
	v_mfma_f32_16x16x32_bf16 v[46:49], v[142:145], v[168:171], 0
	v_mfma_f32_16x16x32_bf16 v[42:45], v[152:155], v[168:171], 0
	v_mfma_f32_16x16x32_bf16 v[30:33], v[142:145], v[176:179], 0
	v_mfma_f32_16x16x32_bf16 v[26:29], v[152:155], v[176:179], 0
	v_mfma_f32_16x16x32_bf16 v[14:17], v[142:145], v[184:187], 0
	v_mfma_f32_16x16x32_bf16 v[10:13], v[152:155], v[184:187], 0
	v_mfma_f32_16x16x32_bf16 v[62:65], v[146:149], v[164:167], v[62:65]
	v_mfma_f32_16x16x32_bf16 v[58:61], v[156:159], v[164:167], v[58:61]
	v_mfma_f32_16x16x32_bf16 v[46:49], v[146:149], v[172:175], v[46:49]
	v_mfma_f32_16x16x32_bf16 v[42:45], v[156:159], v[172:175], v[42:45]
	v_mfma_f32_16x16x32_bf16 v[30:33], v[146:149], v[180:183], v[30:33]
	v_mfma_f32_16x16x32_bf16 v[26:29], v[156:159], v[180:183], v[26:29]
	v_mfma_f32_16x16x32_bf16 v[14:17], v[146:149], v[190:193], v[14:17]
	v_mfma_f32_16x16x32_bf16 v[10:13], v[156:159], v[190:193], v[10:13]
	s_barrier
	s_add_u32 s86, s12, 0x40000
	s_addc_u32 s87, s13, 0
	s_add_i32 m0, s22, 0x14000
	s_nop 0
	global_load_lds_dwordx4 v134, s[86:87]
	s_add_i32 m0, s22, 0x16000
	s_nop 0
	global_load_lds_dwordx4 v130, s[86:87]
	ds_read_b128 v[142:145], v189 offset:32768
	ds_read_b128 v[146:149], v189 offset:33792
	ds_read_b128 v[152:155], v189 offset:34816
	ds_read_b128 v[156:159], v189 offset:35840
	s_waitcnt vmcnt(6)
	s_barrier
	v_mfma_f32_16x16x32_bf16 v[54:57], v[194:197], v[160:163], 0
	v_mfma_f32_16x16x32_bf16 v[50:53], v[202:205], v[160:163], 0
	v_mfma_f32_16x16x32_bf16 v[38:41], v[194:197], v[168:171], 0
	v_mfma_f32_16x16x32_bf16 v[34:37], v[202:205], v[168:171], 0
	v_mfma_f32_16x16x32_bf16 v[22:25], v[194:197], v[176:179], 0
	v_mfma_f32_16x16x32_bf16 v[18:21], v[202:205], v[176:179], 0
	v_mfma_f32_16x16x32_bf16 v[6:9], v[194:197], v[184:187], 0
	v_mfma_f32_16x16x32_bf16 v[2:5], v[202:205], v[184:187], 0
	v_mfma_f32_16x16x32_bf16 v[54:57], v[198:201], v[164:167], v[54:57]
	v_mfma_f32_16x16x32_bf16 v[50:53], v[206:209], v[164:167], v[50:53]
	v_mfma_f32_16x16x32_bf16 v[38:41], v[198:201], v[172:175], v[38:41]
	v_mfma_f32_16x16x32_bf16 v[34:37], v[206:209], v[172:175], v[34:37]
	v_mfma_f32_16x16x32_bf16 v[22:25], v[198:201], v[180:183], v[22:25]
	v_mfma_f32_16x16x32_bf16 v[18:21], v[206:209], v[180:183], v[18:21]
	v_mfma_f32_16x16x32_bf16 v[6:9], v[198:201], v[190:193], v[6:9]
	v_mfma_f32_16x16x32_bf16 v[2:5], v[206:209], v[190:193], v[2:5]
	s_barrier
	s_add_u32 s14, s14, 0x40000
	s_addc_u32 s15, s15, 0
	s_mov_b32 m0, s28
	ds_read_b128 v[160:163], v151 offset:32768
	ds_read_b128 v[164:167], v151 offset:33792
	ds_read_b128 v[168:171], v151 offset:34816
	ds_read_b128 v[172:175], v151 offset:35840
	ds_read_b128 v[176:179], v151 offset:36864
	ds_read_b128 v[180:183], v151 offset:37888
	ds_read_b128 v[184:187], v151 offset:38912
	global_load_lds_dwordx4 v136, s[14:15]
	s_mov_b32 m0, s29
	ds_read_b128 v[190:193], v151 offset:39936
	global_load_lds_dwordx4 v132, s[14:15]
	s_waitcnt lgkmcnt(8)
	s_barrier
	s_waitcnt lgkmcnt(0)
	v_mfma_f32_16x16x32_bf16 v[126:129], v[142:145], v[160:163], v[126:129]
	v_mfma_f32_16x16x32_bf16 v[122:125], v[152:155], v[160:163], v[122:125]
	v_mfma_f32_16x16x32_bf16 v[110:113], v[142:145], v[168:171], v[110:113]
	v_mfma_f32_16x16x32_bf16 v[106:109], v[152:155], v[168:171], v[106:109]
	v_mfma_f32_16x16x32_bf16 v[94:97], v[142:145], v[176:179], v[94:97]
	v_mfma_f32_16x16x32_bf16 v[90:93], v[152:155], v[176:179], v[90:93]
	v_mfma_f32_16x16x32_bf16 v[78:81], v[142:145], v[184:187], v[78:81]
	v_mfma_f32_16x16x32_bf16 v[74:77], v[152:155], v[184:187], v[74:77]
	v_mfma_f32_16x16x32_bf16 v[126:129], v[146:149], v[164:167], v[126:129]
	v_mfma_f32_16x16x32_bf16 v[122:125], v[156:159], v[164:167], v[122:125]
	v_mfma_f32_16x16x32_bf16 v[110:113], v[146:149], v[172:175], v[110:113]
	v_mfma_f32_16x16x32_bf16 v[106:109], v[156:159], v[172:175], v[106:109]
	v_mfma_f32_16x16x32_bf16 v[94:97], v[146:149], v[180:183], v[94:97]
	v_mfma_f32_16x16x32_bf16 v[90:93], v[156:159], v[180:183], v[90:93]
	v_mfma_f32_16x16x32_bf16 v[78:81], v[146:149], v[190:193], v[78:81]
	v_mfma_f32_16x16x32_bf16 v[74:77], v[156:159], v[190:193], v[74:77]
	s_barrier
	s_add_i32 m0, s22, 0x18000
	ds_read_b128 v[194:197], v189 offset:49152
	ds_read_b128 v[198:201], v189 offset:50176
	ds_read_b128 v[202:205], v189 offset:51200
	ds_read_b128 v[206:209], v189 offset:52224
	s_add_u32 s98, s12, s40
	s_addc_u32 s99, s13, s41
	global_load_lds_dwordx4 v134, s[98:99]
	s_add_i32 m0, s22, 0x1a000
	s_nop 0
	global_load_lds_dwordx4 v130, s[98:99]
	s_barrier
	s_waitcnt lgkmcnt(0)
	v_mfma_f32_16x16x32_bf16 v[118:121], v[194:197], v[160:163], v[118:121]
	v_mfma_f32_16x16x32_bf16 v[114:117], v[202:205], v[160:163], v[114:117]
	v_mfma_f32_16x16x32_bf16 v[102:105], v[194:197], v[168:171], v[102:105]
	v_mfma_f32_16x16x32_bf16 v[98:101], v[202:205], v[168:171], v[98:101]
	v_mfma_f32_16x16x32_bf16 v[86:89], v[194:197], v[176:179], v[86:89]
	v_mfma_f32_16x16x32_bf16 v[82:85], v[202:205], v[176:179], v[82:85]
	v_mfma_f32_16x16x32_bf16 v[70:73], v[194:197], v[184:187], v[70:73]
	v_mfma_f32_16x16x32_bf16 v[66:69], v[202:205], v[184:187], v[66:69]
	v_mfma_f32_16x16x32_bf16 v[118:121], v[198:201], v[164:167], v[118:121]
	v_mfma_f32_16x16x32_bf16 v[114:117], v[206:209], v[164:167], v[114:117]
	v_mfma_f32_16x16x32_bf16 v[102:105], v[198:201], v[172:175], v[102:105]
	v_mfma_f32_16x16x32_bf16 v[98:101], v[206:209], v[172:175], v[98:101]
	v_mfma_f32_16x16x32_bf16 v[86:89], v[198:201], v[180:183], v[86:89]
	v_mfma_f32_16x16x32_bf16 v[82:85], v[206:209], v[180:183], v[82:85]
	v_mfma_f32_16x16x32_bf16 v[70:73], v[198:201], v[190:193], v[70:73]
	v_mfma_f32_16x16x32_bf16 v[66:69], v[206:209], v[190:193], v[66:69]
	s_mov_b32 m0, s38
	s_barrier
	ds_read_b128 v[160:163], v151 offset:49152
	ds_read_b128 v[164:167], v151 offset:50176
	ds_read_b128 v[168:171], v151 offset:51200
	ds_read_b128 v[172:175], v151 offset:52224
	ds_read_b128 v[176:179], v151 offset:53248
	ds_read_b128 v[180:183], v151 offset:54272
	ds_read_b128 v[184:187], v151 offset:55296
	ds_read_b128 v[190:193], v151 offset:56320
	s_add_u32 s98, s100, s40
	s_addc_u32 s99, s101, s41
	global_load_lds_dwordx4 v136, s[98:99]
	s_mov_b32 m0, s39
	s_nop 0
	global_load_lds_dwordx4 v132, s[98:99]
	s_waitcnt vmcnt(10)
	s_barrier
	s_waitcnt lgkmcnt(0)
	v_mfma_f32_16x16x32_bf16 v[62:65], v[142:145], v[160:163], v[62:65]
	v_mfma_f32_16x16x32_bf16 v[58:61], v[152:155], v[160:163], v[58:61]
	v_mfma_f32_16x16x32_bf16 v[46:49], v[142:145], v[168:171], v[46:49]
	v_mfma_f32_16x16x32_bf16 v[42:45], v[152:155], v[168:171], v[42:45]
	v_mfma_f32_16x16x32_bf16 v[30:33], v[142:145], v[176:179], v[30:33]
	v_mfma_f32_16x16x32_bf16 v[26:29], v[152:155], v[176:179], v[26:29]
	v_mfma_f32_16x16x32_bf16 v[14:17], v[142:145], v[184:187], v[14:17]
	v_mfma_f32_16x16x32_bf16 v[10:13], v[152:155], v[184:187], v[10:13]
	v_mfma_f32_16x16x32_bf16 v[62:65], v[146:149], v[164:167], v[62:65]
	v_mfma_f32_16x16x32_bf16 v[58:61], v[156:159], v[164:167], v[58:61]
	v_mfma_f32_16x16x32_bf16 v[46:49], v[146:149], v[172:175], v[46:49]
	v_mfma_f32_16x16x32_bf16 v[42:45], v[156:159], v[172:175], v[42:45]
	v_mfma_f32_16x16x32_bf16 v[30:33], v[146:149], v[180:183], v[30:33]
	v_mfma_f32_16x16x32_bf16 v[26:29], v[156:159], v[180:183], v[26:29]
	v_mfma_f32_16x16x32_bf16 v[14:17], v[146:149], v[190:193], v[14:17]
	v_mfma_f32_16x16x32_bf16 v[10:13], v[156:159], v[190:193], v[10:13]
	s_barrier
	s_add_u32 s12, s12, 0x40080
	s_addc_u32 s13, s13, 0
	s_add_i32 m0, s22, 0x1c000
	s_nop 0
	global_load_lds_dwordx4 v134, s[12:13]
	s_add_i32 m0, s22, 0x1e000
	s_nop 0
	global_load_lds_dwordx4 v130, s[12:13]
	ds_read_b128 v[142:145], v189
	ds_read_b128 v[146:149], v189 offset:1024
	ds_read_b128 v[152:155], v189 offset:2048
	ds_read_b128 v[156:159], v189 offset:3072
	s_waitcnt vmcnt(6)
	s_barrier
	v_mfma_f32_16x16x32_bf16 v[54:57], v[194:197], v[160:163], v[54:57]
	v_mfma_f32_16x16x32_bf16 v[50:53], v[202:205], v[160:163], v[50:53]
	v_mfma_f32_16x16x32_bf16 v[38:41], v[194:197], v[168:171], v[38:41]
	v_mfma_f32_16x16x32_bf16 v[34:37], v[202:205], v[168:171], v[34:37]
	v_mfma_f32_16x16x32_bf16 v[22:25], v[194:197], v[176:179], v[22:25]
	v_mfma_f32_16x16x32_bf16 v[18:21], v[202:205], v[176:179], v[18:21]
	v_mfma_f32_16x16x32_bf16 v[6:9], v[194:197], v[184:187], v[6:9]
	v_mfma_f32_16x16x32_bf16 v[2:5], v[202:205], v[184:187], v[2:5]
	v_mfma_f32_16x16x32_bf16 v[54:57], v[198:201], v[164:167], v[54:57]
	v_mfma_f32_16x16x32_bf16 v[50:53], v[206:209], v[164:167], v[50:53]
	v_mfma_f32_16x16x32_bf16 v[38:41], v[198:201], v[172:175], v[38:41]
	v_mfma_f32_16x16x32_bf16 v[34:37], v[206:209], v[172:175], v[34:37]
	v_mfma_f32_16x16x32_bf16 v[22:25], v[198:201], v[180:183], v[22:25]
	v_mfma_f32_16x16x32_bf16 v[18:21], v[206:209], v[180:183], v[18:21]
	v_mfma_f32_16x16x32_bf16 v[6:9], v[198:201], v[190:193], v[6:9]
	v_mfma_f32_16x16x32_bf16 v[2:5], v[206:209], v[190:193], v[2:5]
	s_add_i32 s85, s85, 2
	s_add_u32 s4, s4, 0x100
	s_addc_u32 s5, s5, 0
	s_add_u32 s78, s78, 0x100
	s_addc_u32 s79, s79, 0
	s_add_u32 s12, s4, 0xfffc0080
	s_addc_u32 s13, s5, -1
	s_cmp_eq_u32 s85, 12
	s_cselect_b32 s15, s44, s13
	s_cselect_b32 s14, s45, s12
	s_cselect_b32 s13, s47, s79
	s_cselect_b32 s12, s55, s78
	s_cmp_gt_u32 s85, 13
	s_barrier
	.p2align 6
	s_nop 0
	s_nop 0
	s_nop 0
	s_nop 0
	s_nop 0
	s_nop 0
	s_nop 0
	s_nop 0

.LBB0_837:
	s_ashr_i32 s15, s14, 31
	s_lshl_b64 s[78:79], s[14:15], 19
	s_add_u32 s84, s36, s78
	s_addc_u32 s85, s37, s79
	s_and_b64 s[4:5], s[4:5], exec
	s_cselect_b32 s15, s85, s91
	s_cselect_b32 s23, s84, s90
	s_add_u32 s34, s90, 0x100
	s_addc_u32 s75, s91, 0
	s_mov_b32 s78, -2
	s_waitcnt lgkmcnt(0)
	s_add_i32 s79, 0, 0x10000
	v_add_u32_e32 v142, s79, v212
	v_add_u32_e32 v189, 0x10000, v212
	ds_read_b128 v[130:133], v142
	ds_read_b128 v[134:137], v142 offset:1024
	ds_read_b128 v[138:141], v142 offset:2048
	ds_read_b128 v[142:145], v142 offset:3072
	s_add_u32 s4, s88, 0x100
	s_addc_u32 s5, s89, 0
	s_cmp_eq_u32 s78, 12
	s_cselect_b32 s93, s17, s5
	s_cselect_b32 s92, s16, s4
	s_cselect_b32 s91, s15, s75
	s_cselect_b32 s90, s23, s34
	v_lshl_add_u64 v[178:179], s[88:89], 0, v[196:197]
	s_add_i32 m0, s39, 0xc000
	ds_read_b128 v[146:149], v213
	ds_read_b128 v[150:153], v213 offset:1024
	ds_read_b128 v[154:157], v213 offset:2048
	ds_read_b128 v[158:161], v213 offset:3072
	ds_read_b128 v[162:165], v213 offset:4096
	ds_read_b128 v[166:169], v213 offset:5120
	ds_read_b128 v[170:173], v213 offset:6144
	ds_read_b128 v[174:177], v213 offset:7168
	global_load_lds_dwordx4 v[178:179], off
	s_add_i32 m0, s39, 0xe000
	v_lshl_add_u64 v[178:179], s[88:89], 0, v[198:199]
	global_load_lds_dwordx4 v[178:179], off
	s_waitcnt lgkmcnt(8)
	s_barrier
	s_waitcnt lgkmcnt(0)
	v_mfma_f32_16x16x32_bf16 v[126:129], v[130:133], v[146:149], 0
	v_mfma_f32_16x16x32_bf16 v[122:125], v[138:141], v[146:149], 0
	v_mfma_f32_16x16x32_bf16 v[110:113], v[130:133], v[154:157], 0
	v_mfma_f32_16x16x32_bf16 v[106:109], v[138:141], v[154:157], 0
	v_mfma_f32_16x16x32_bf16 v[94:97], v[130:133], v[162:165], 0
	v_mfma_f32_16x16x32_bf16 v[90:93], v[138:141], v[162:165], 0
	v_mfma_f32_16x16x32_bf16 v[78:81], v[130:133], v[170:173], 0
	v_mfma_f32_16x16x32_bf16 v[74:77], v[138:141], v[170:173], 0
	v_mfma_f32_16x16x32_bf16 v[126:129], v[134:137], v[150:153], v[126:129]
	v_mfma_f32_16x16x32_bf16 v[122:125], v[142:145], v[150:153], v[122:125]
	v_mfma_f32_16x16x32_bf16 v[110:113], v[134:137], v[158:161], v[110:113]
	v_mfma_f32_16x16x32_bf16 v[106:109], v[142:145], v[158:161], v[106:109]
	v_mfma_f32_16x16x32_bf16 v[94:97], v[134:137], v[166:169], v[94:97]
	v_mfma_f32_16x16x32_bf16 v[90:93], v[142:145], v[166:169], v[90:93]
	v_mfma_f32_16x16x32_bf16 v[78:81], v[134:137], v[174:177], v[78:81]
	v_mfma_f32_16x16x32_bf16 v[74:77], v[142:145], v[174:177], v[74:77]
	s_barrier
	ds_read_b128 v[178:181], v189 offset:16384
	ds_read_b128 v[182:185], v189 offset:17408
	ds_read_b128 v[200:203], v189 offset:18432
	ds_read_b128 v[204:207], v189 offset:19456
	s_add_i32 m0, s38, 0x10000
	s_nop 0
	global_load_lds_dwordx4 v0, s[90:91]
	s_add_i32 m0, s38, 0x12000
	s_nop 0
	global_load_lds_dwordx4 v194, s[90:91]
	s_barrier
	s_waitcnt lgkmcnt(0)
	v_mfma_f32_16x16x32_bf16 v[118:121], v[178:181], v[146:149], 0
	v_mfma_f32_16x16x32_bf16 v[114:117], v[200:203], v[146:149], 0
	v_mfma_f32_16x16x32_bf16 v[102:105], v[178:181], v[154:157], 0
	v_mfma_f32_16x16x32_bf16 v[98:101], v[200:203], v[154:157], 0
	v_mfma_f32_16x16x32_bf16 v[86:89], v[178:181], v[162:165], 0
	v_mfma_f32_16x16x32_bf16 v[82:85], v[200:203], v[162:165], 0
	v_mfma_f32_16x16x32_bf16 v[70:73], v[178:181], v[170:173], 0
	v_mfma_f32_16x16x32_bf16 v[66:69], v[200:203], v[170:173], 0
	v_mfma_f32_16x16x32_bf16 v[118:121], v[182:185], v[150:153], v[118:121]
	v_mfma_f32_16x16x32_bf16 v[114:117], v[204:207], v[150:153], v[114:117]
	v_mfma_f32_16x16x32_bf16 v[102:105], v[182:185], v[158:161], v[102:105]
	v_mfma_f32_16x16x32_bf16 v[98:101], v[204:207], v[158:161], v[98:101]
	v_mfma_f32_16x16x32_bf16 v[86:89], v[182:185], v[166:169], v[86:89]
	v_mfma_f32_16x16x32_bf16 v[82:85], v[204:207], v[166:169], v[82:85]
	v_mfma_f32_16x16x32_bf16 v[70:73], v[182:185], v[174:177], v[70:73]
	v_mfma_f32_16x16x32_bf16 v[66:69], v[204:207], v[174:177], v[66:69]
	s_mov_b32 m0, s39
	s_barrier
	ds_read_b128 v[146:149], v213 offset:16384
	ds_read_b128 v[150:153], v213 offset:17408
	ds_read_b128 v[154:157], v213 offset:18432
	ds_read_b128 v[158:161], v213 offset:19456
	ds_read_b128 v[162:165], v213 offset:20480
	ds_read_b128 v[166:169], v213 offset:21504
	ds_read_b128 v[170:173], v213 offset:22528
	global_load_lds_dwordx4 v190, s[92:93]
	s_mov_b32 m0, s42
	ds_read_b128 v[174:177], v213 offset:23552
	global_load_lds_dwordx4 v192, s[92:93]
	s_waitcnt vmcnt(10)
	s_barrier
	s_waitcnt lgkmcnt(0)
	v_mfma_f32_16x16x32_bf16 v[62:65], v[130:133], v[146:149], 0
	v_mfma_f32_16x16x32_bf16 v[58:61], v[138:141], v[146:149], 0
	v_mfma_f32_16x16x32_bf16 v[46:49], v[130:133], v[154:157], 0
	v_mfma_f32_16x16x32_bf16 v[42:45], v[138:141], v[154:157], 0
	v_mfma_f32_16x16x32_bf16 v[30:33], v[130:133], v[162:165], 0
	v_mfma_f32_16x16x32_bf16 v[26:29], v[138:141], v[162:165], 0
	v_mfma_f32_16x16x32_bf16 v[14:17], v[130:133], v[170:173], 0
	v_mfma_f32_16x16x32_bf16 v[10:13], v[138:141], v[170:173], 0
	v_mfma_f32_16x16x32_bf16 v[62:65], v[134:137], v[150:153], v[62:65]
	v_mfma_f32_16x16x32_bf16 v[58:61], v[142:145], v[150:153], v[58:61]
	v_mfma_f32_16x16x32_bf16 v[46:49], v[134:137], v[158:161], v[46:49]
	v_mfma_f32_16x16x32_bf16 v[42:45], v[142:145], v[158:161], v[42:45]
	v_mfma_f32_16x16x32_bf16 v[30:33], v[134:137], v[166:169], v[30:33]
	v_mfma_f32_16x16x32_bf16 v[26:29], v[142:145], v[166:169], v[26:29]
	v_mfma_f32_16x16x32_bf16 v[14:17], v[134:137], v[174:177], v[14:17]
	v_mfma_f32_16x16x32_bf16 v[10:13], v[142:145], v[174:177], v[10:13]
	s_barrier
	s_add_u32 s88, s90, 0x40000
	s_addc_u32 s89, s91, 0
	s_add_i32 m0, s38, 0x14000
	s_nop 0
	global_load_lds_dwordx4 v0, s[88:89]
	s_add_i32 m0, s38, 0x16000
	s_nop 0
	global_load_lds_dwordx4 v194, s[88:89]
	s_add_i32 s79, 0, 0x18000
	v_add_u32_e32 v142, s79, v212
	ds_read_b128 v[130:133], v142
	ds_read_b128 v[134:137], v142 offset:1024
	ds_read_b128 v[138:141], v142 offset:2048
	ds_read_b128 v[142:145], v142 offset:3072
	s_waitcnt vmcnt(6)
	s_barrier
	v_mfma_f32_16x16x32_bf16 v[54:57], v[178:181], v[146:149], 0
	v_mfma_f32_16x16x32_bf16 v[50:53], v[200:203], v[146:149], 0
	v_mfma_f32_16x16x32_bf16 v[38:41], v[178:181], v[154:157], 0
	v_mfma_f32_16x16x32_bf16 v[34:37], v[200:203], v[154:157], 0
	v_mfma_f32_16x16x32_bf16 v[22:25], v[178:181], v[162:165], 0
	v_mfma_f32_16x16x32_bf16 v[18:21], v[200:203], v[162:165], 0
	v_mfma_f32_16x16x32_bf16 v[6:9], v[178:181], v[170:173], 0
	v_mfma_f32_16x16x32_bf16 v[2:5], v[200:203], v[170:173], 0
	v_mfma_f32_16x16x32_bf16 v[54:57], v[182:185], v[150:153], v[54:57]
	v_mfma_f32_16x16x32_bf16 v[50:53], v[204:207], v[150:153], v[50:53]
	v_mfma_f32_16x16x32_bf16 v[38:41], v[182:185], v[158:161], v[38:41]
	v_mfma_f32_16x16x32_bf16 v[34:37], v[204:207], v[158:161], v[34:37]
	v_mfma_f32_16x16x32_bf16 v[22:25], v[182:185], v[166:169], v[22:25]
	v_mfma_f32_16x16x32_bf16 v[18:21], v[204:207], v[166:169], v[18:21]
	v_mfma_f32_16x16x32_bf16 v[6:9], v[182:185], v[174:177], v[6:9]
	v_mfma_f32_16x16x32_bf16 v[2:5], v[204:207], v[174:177], v[2:5]
	s_barrier
	s_add_u32 s88, s92, 0xc0000
	s_addc_u32 s89, s93, 0
	s_mov_b32 m0, s43
	ds_read_b128 v[146:149], v213 offset:32768
	ds_read_b128 v[150:153], v213 offset:33792
	ds_read_b128 v[154:157], v213 offset:34816
	ds_read_b128 v[158:161], v213 offset:35840
	ds_read_b128 v[162:165], v213 offset:36864
	ds_read_b128 v[166:169], v213 offset:37888
	ds_read_b128 v[170:173], v213 offset:38912
	global_load_lds_dwordx4 v190, s[88:89]
	s_mov_b32 m0, s44
	ds_read_b128 v[174:177], v213 offset:39936
	global_load_lds_dwordx4 v192, s[88:89]
	s_waitcnt lgkmcnt(8)
	s_barrier
	s_waitcnt lgkmcnt(0)
	v_mfma_f32_16x16x32_bf16 v[126:129], v[130:133], v[146:149], v[126:129]
	v_mfma_f32_16x16x32_bf16 v[122:125], v[138:141], v[146:149], v[122:125]
	v_mfma_f32_16x16x32_bf16 v[110:113], v[130:133], v[154:157], v[110:113]
	v_mfma_f32_16x16x32_bf16 v[106:109], v[138:141], v[154:157], v[106:109]
	v_mfma_f32_16x16x32_bf16 v[94:97], v[130:133], v[162:165], v[94:97]
	v_mfma_f32_16x16x32_bf16 v[90:93], v[138:141], v[162:165], v[90:93]
	v_mfma_f32_16x16x32_bf16 v[78:81], v[130:133], v[170:173], v[78:81]
	v_mfma_f32_16x16x32_bf16 v[74:77], v[138:141], v[170:173], v[74:77]
	v_mfma_f32_16x16x32_bf16 v[126:129], v[134:137], v[150:153], v[126:129]
	v_mfma_f32_16x16x32_bf16 v[122:125], v[142:145], v[150:153], v[122:125]
	v_mfma_f32_16x16x32_bf16 v[110:113], v[134:137], v[158:161], v[110:113]
	v_mfma_f32_16x16x32_bf16 v[106:109], v[142:145], v[158:161], v[106:109]
	v_mfma_f32_16x16x32_bf16 v[94:97], v[134:137], v[166:169], v[94:97]
	v_mfma_f32_16x16x32_bf16 v[90:93], v[142:145], v[166:169], v[90:93]
	v_mfma_f32_16x16x32_bf16 v[78:81], v[134:137], v[174:177], v[78:81]
	v_mfma_f32_16x16x32_bf16 v[74:77], v[142:145], v[174:177], v[74:77]
	s_barrier
	s_add_i32 s87, 0, 0x1c000
	v_add_u32_e32 v204, s87, v212
	s_add_i32 m0, s38, 0x18000
	ds_read_b128 v[178:181], v204
	ds_read_b128 v[182:185], v204 offset:1024
	ds_read_b128 v[200:203], v204 offset:2048
	ds_read_b128 v[204:207], v204 offset:3072
	s_add_u32 s98, s90, s40
	s_addc_u32 s99, s91, s41
	global_load_lds_dwordx4 v0, s[98:99]
	s_add_i32 m0, s38, 0x1a000
	s_nop 0
	global_load_lds_dwordx4 v194, s[98:99]
	s_barrier
	s_waitcnt lgkmcnt(0)
	v_mfma_f32_16x16x32_bf16 v[118:121], v[178:181], v[146:149], v[118:121]
	v_mfma_f32_16x16x32_bf16 v[114:117], v[200:203], v[146:149], v[114:117]
	v_mfma_f32_16x16x32_bf16 v[102:105], v[178:181], v[154:157], v[102:105]
	v_mfma_f32_16x16x32_bf16 v[98:101], v[200:203], v[154:157], v[98:101]
	v_mfma_f32_16x16x32_bf16 v[86:89], v[178:181], v[162:165], v[86:89]
	v_mfma_f32_16x16x32_bf16 v[82:85], v[200:203], v[162:165], v[82:85]
	v_mfma_f32_16x16x32_bf16 v[70:73], v[178:181], v[170:173], v[70:73]
	v_mfma_f32_16x16x32_bf16 v[66:69], v[200:203], v[170:173], v[66:69]
	v_mfma_f32_16x16x32_bf16 v[118:121], v[182:185], v[150:153], v[118:121]
	v_mfma_f32_16x16x32_bf16 v[114:117], v[204:207], v[150:153], v[114:117]
	v_mfma_f32_16x16x32_bf16 v[102:105], v[182:185], v[158:161], v[102:105]
	v_mfma_f32_16x16x32_bf16 v[98:101], v[204:207], v[158:161], v[98:101]
	v_mfma_f32_16x16x32_bf16 v[86:89], v[182:185], v[166:169], v[86:89]
	v_mfma_f32_16x16x32_bf16 v[82:85], v[204:207], v[166:169], v[82:85]
	v_mfma_f32_16x16x32_bf16 v[70:73], v[182:185], v[174:177], v[70:73]
	v_mfma_f32_16x16x32_bf16 v[66:69], v[204:207], v[174:177], v[66:69]
	s_mov_b32 m0, s60
	s_barrier
	ds_read_b128 v[146:149], v213 offset:49152
	ds_read_b128 v[150:153], v213 offset:50176
	ds_read_b128 v[154:157], v213 offset:51200
	ds_read_b128 v[158:161], v213 offset:52224
	ds_read_b128 v[162:165], v213 offset:53248
	ds_read_b128 v[166:169], v213 offset:54272
	ds_read_b128 v[170:173], v213 offset:55296
	ds_read_b128 v[174:177], v213 offset:56320
	s_add_u32 s98, s92, s40
	s_addc_u32 s99, s93, s41
	global_load_lds_dwordx4 v190, s[98:99]
	s_mov_b32 m0, s61
	s_nop 0
	global_load_lds_dwordx4 v192, s[98:99]
	s_waitcnt vmcnt(10)
	s_barrier
	s_waitcnt lgkmcnt(0)
	v_mfma_f32_16x16x32_bf16 v[62:65], v[130:133], v[146:149], v[62:65]
	v_mfma_f32_16x16x32_bf16 v[58:61], v[138:141], v[146:149], v[58:61]
	v_mfma_f32_16x16x32_bf16 v[46:49], v[130:133], v[154:157], v[46:49]
	v_mfma_f32_16x16x32_bf16 v[42:45], v[138:141], v[154:157], v[42:45]
	v_mfma_f32_16x16x32_bf16 v[30:33], v[130:133], v[162:165], v[30:33]
	v_mfma_f32_16x16x32_bf16 v[26:29], v[138:141], v[162:165], v[26:29]
	v_mfma_f32_16x16x32_bf16 v[14:17], v[130:133], v[170:173], v[14:17]
	v_mfma_f32_16x16x32_bf16 v[10:13], v[138:141], v[170:173], v[10:13]
	v_mfma_f32_16x16x32_bf16 v[62:65], v[134:137], v[150:153], v[62:65]
	v_mfma_f32_16x16x32_bf16 v[58:61], v[142:145], v[150:153], v[58:61]
	v_mfma_f32_16x16x32_bf16 v[46:49], v[134:137], v[158:161], v[46:49]
	v_mfma_f32_16x16x32_bf16 v[42:45], v[142:145], v[158:161], v[42:45]
	v_mfma_f32_16x16x32_bf16 v[30:33], v[134:137], v[166:169], v[30:33]
	v_mfma_f32_16x16x32_bf16 v[26:29], v[142:145], v[166:169], v[26:29]
	v_mfma_f32_16x16x32_bf16 v[14:17], v[134:137], v[174:177], v[14:17]
	v_mfma_f32_16x16x32_bf16 v[10:13], v[142:145], v[174:177], v[10:13]
	s_barrier
	s_add_u32 s88, s90, 0x40080
	s_addc_u32 s89, s91, 0
	s_add_i32 m0, s38, 0x1c000
	s_nop 0
	global_load_lds_dwordx4 v0, s[88:89]
	s_add_i32 m0, s38, 0x1e000
	s_nop 0
	global_load_lds_dwordx4 v194, s[88:89]
	ds_read_b128 v[130:133], v189
	ds_read_b128 v[134:137], v189 offset:1024
	ds_read_b128 v[138:141], v189 offset:2048
	ds_read_b128 v[142:145], v189 offset:3072
	s_waitcnt vmcnt(6)
	s_barrier
	v_mfma_f32_16x16x32_bf16 v[54:57], v[178:181], v[146:149], v[54:57]
	v_mfma_f32_16x16x32_bf16 v[50:53], v[200:203], v[146:149], v[50:53]
	v_mfma_f32_16x16x32_bf16 v[38:41], v[178:181], v[154:157], v[38:41]
	v_mfma_f32_16x16x32_bf16 v[34:37], v[200:203], v[154:157], v[34:37]
	v_mfma_f32_16x16x32_bf16 v[22:25], v[178:181], v[162:165], v[22:25]
	v_mfma_f32_16x16x32_bf16 v[18:21], v[200:203], v[162:165], v[18:21]
	v_mfma_f32_16x16x32_bf16 v[6:9], v[178:181], v[170:173], v[6:9]
	v_mfma_f32_16x16x32_bf16 v[2:5], v[200:203], v[170:173], v[2:5]
	v_mfma_f32_16x16x32_bf16 v[54:57], v[182:185], v[150:153], v[54:57]
	v_mfma_f32_16x16x32_bf16 v[50:53], v[204:207], v[150:153], v[50:53]
	v_mfma_f32_16x16x32_bf16 v[38:41], v[182:185], v[158:161], v[38:41]
	v_mfma_f32_16x16x32_bf16 v[34:37], v[204:207], v[158:161], v[34:37]
	v_mfma_f32_16x16x32_bf16 v[22:25], v[182:185], v[166:169], v[22:25]
	v_mfma_f32_16x16x32_bf16 v[18:21], v[204:207], v[166:169], v[18:21]
	v_mfma_f32_16x16x32_bf16 v[6:9], v[182:185], v[174:177], v[6:9]
	v_mfma_f32_16x16x32_bf16 v[2:5], v[204:207], v[174:177], v[2:5]
	s_add_i32 s78, s78, 2
	s_add_u32 s34, s34, 0x100
	s_addc_u32 s75, s75, 0
	s_mov_b64 s[88:89], s[4:5]
	s_add_u32 s4, s88, 0x100
	s_addc_u32 s5, s89, 0
	s_cmp_eq_u32 s78, 12
	s_cselect_b32 s93, s17, s5
	s_cselect_b32 s92, s16, s4
	s_cselect_b32 s91, s15, s75
	s_cselect_b32 s90, s23, s34
	s_cmp_gt_u32 s78, 13
	s_barrier
	.p2align 6
	s_nop 0
	s_nop 0
	s_nop 0
	s_nop 0
	s_nop 0
	s_nop 0
	s_nop 0
	s_nop 0

.LBB0_918:
	s_ashr_i32 s17, s16, 31
	s_lshl_b64 s[22:23], s[16:17], 19
	v_mov_b64_e32 v[2:3], 0xb00
	s_add_u32 s84, s8, s22
	v_cmp_lt_i64_e32 vcc, s[28:29], v[2:3]
	s_addc_u32 s85, s9, s23
	s_and_b64 s[22:23], vcc, exec
	s_cselect_b32 s17, s85, s7
	s_cselect_b32 s22, s84, s6
	s_ashr_i32 s15, s14, 31
	s_lshl_b64 s[28:29], s[14:15], 19
	s_add_u32 s86, s37, s28
	s_addc_u32 s87, s38, s29
	s_and_b64 s[28:29], vcc, exec
	s_cselect_b32 s15, s87, s89
	s_cselect_b32 s23, s86, s88
	s_add_u32 s28, s88, 0x100
	s_addc_u32 s29, s89, 0
	s_mov_b32 s45, -2
	s_add_i32 vcc_lo, 0, 0x10000
	v_add_u32_e32 v0, vcc_lo, v254
	v_add_u32_e32 v189, 0x10000, v254
	ds_read_b128 v[130:133], v0
	ds_read_b128 v[134:137], v0 offset:1024
	ds_read_b128 v[138:141], v0 offset:2048
	ds_read_b128 v[142:145], v0 offset:3072
	s_add_u32 s88, s6, 0x100
	s_addc_u32 s89, s7, 0
	s_cmp_eq_u32 s45, 12
	s_cselect_b32 s93, s17, s89
	s_cselect_b32 s92, s22, s88
	s_cselect_b32 s91, s15, s29
	s_cselect_b32 s90, s23, s28
	s_add_i32 m0, s43, 0xc000
	ds_read_b128 v[146:149], v253
	ds_read_b128 v[150:153], v253 offset:1024
	ds_read_b128 v[168:171], v253 offset:2048
	ds_read_b128 v[172:175], v253 offset:3072
	ds_read_b128 v[176:179], v253 offset:4096
	ds_read_b128 v[180:183], v253 offset:5120
	ds_read_b128 v[184:187], v253 offset:6144
	ds_read_b128 v[190:193], v253 offset:7168
	global_load_lds_dwordx4 v164, s[6:7]
	s_add_i32 m0, s43, 0xe000
	v_lshl_add_u64 v[154:155], s[6:7], 0, v[166:167]
	global_load_lds_dwordx4 v[154:155], off
	s_waitcnt lgkmcnt(8)
	s_barrier
	s_waitcnt lgkmcnt(0)
	v_mfma_f32_16x16x32_bf16 v[126:129], v[130:133], v[146:149], 0
	v_mfma_f32_16x16x32_bf16 v[70:73], v[138:141], v[146:149], 0
	v_mfma_f32_16x16x32_bf16 v[122:125], v[130:133], v[168:171], 0
	v_mfma_f32_16x16x32_bf16 v[74:77], v[138:141], v[168:171], 0
	v_mfma_f32_16x16x32_bf16 v[114:117], v[130:133], v[176:179], 0
	v_mfma_f32_16x16x32_bf16 v[66:69], v[138:141], v[176:179], 0
	v_mfma_f32_16x16x32_bf16 v[110:113], v[130:133], v[184:187], 0
	v_mfma_f32_16x16x32_bf16 v[78:81], v[138:141], v[184:187], 0
	v_mfma_f32_16x16x32_bf16 v[126:129], v[134:137], v[150:153], v[126:129]
	v_mfma_f32_16x16x32_bf16 v[70:73], v[142:145], v[150:153], v[70:73]
	v_mfma_f32_16x16x32_bf16 v[122:125], v[134:137], v[172:175], v[122:125]
	v_mfma_f32_16x16x32_bf16 v[74:77], v[142:145], v[172:175], v[74:77]
	v_mfma_f32_16x16x32_bf16 v[114:117], v[134:137], v[180:183], v[114:117]
	v_mfma_f32_16x16x32_bf16 v[66:69], v[142:145], v[180:183], v[66:69]
	v_mfma_f32_16x16x32_bf16 v[110:113], v[134:137], v[190:193], v[110:113]
	v_mfma_f32_16x16x32_bf16 v[78:81], v[142:145], v[190:193], v[78:81]
	s_barrier
	s_add_i32 m0, s39, 0x10000
	ds_read_b128 v[194:197], v189 offset:16384
	ds_read_b128 v[198:201], v189 offset:17408
	ds_read_b128 v[202:205], v189 offset:18432
	global_load_lds_dwordx4 v160, s[90:91]
	s_add_i32 m0, s39, 0x12000
	ds_read_b128 v[206:209], v189 offset:19456
	global_load_lds_dwordx4 v156, s[90:91]
	s_barrier
	s_waitcnt lgkmcnt(0)
	v_mfma_f32_16x16x32_bf16 v[118:121], v[194:197], v[146:149], 0
	v_mfma_f32_16x16x32_bf16 v[94:97], v[202:205], v[146:149], 0
	v_mfma_f32_16x16x32_bf16 v[106:109], v[194:197], v[168:171], 0
	v_mfma_f32_16x16x32_bf16 v[90:93], v[202:205], v[168:171], 0
	v_mfma_f32_16x16x32_bf16 v[102:105], v[194:197], v[176:179], 0
	v_mfma_f32_16x16x32_bf16 v[82:85], v[202:205], v[176:179], 0
	v_mfma_f32_16x16x32_bf16 v[98:101], v[194:197], v[184:187], 0
	v_mfma_f32_16x16x32_bf16 v[86:89], v[202:205], v[184:187], 0
	v_mfma_f32_16x16x32_bf16 v[118:121], v[198:201], v[150:153], v[118:121]
	v_mfma_f32_16x16x32_bf16 v[94:97], v[206:209], v[150:153], v[94:97]
	v_mfma_f32_16x16x32_bf16 v[106:109], v[198:201], v[172:175], v[106:109]
	v_mfma_f32_16x16x32_bf16 v[90:93], v[206:209], v[172:175], v[90:93]
	v_mfma_f32_16x16x32_bf16 v[102:105], v[198:201], v[180:183], v[102:105]
	v_mfma_f32_16x16x32_bf16 v[82:85], v[206:209], v[180:183], v[82:85]
	v_mfma_f32_16x16x32_bf16 v[98:101], v[198:201], v[190:193], v[98:101]
	v_mfma_f32_16x16x32_bf16 v[86:89], v[206:209], v[190:193], v[86:89]
	s_mov_b32 m0, s43
	s_mov_b64 s[100:101], s[92:93]
	s_barrier
	ds_read_b128 v[146:149], v253 offset:16384
	ds_read_b128 v[150:153], v253 offset:17408
	ds_read_b128 v[168:171], v253 offset:18432
	ds_read_b128 v[172:175], v253 offset:19456
	ds_read_b128 v[176:179], v253 offset:20480
	ds_read_b128 v[180:183], v253 offset:21504
	ds_read_b128 v[184:187], v253 offset:22528
	global_load_lds_dwordx4 v162, s[100:101]
	s_mov_b32 m0, s60
	ds_read_b128 v[190:193], v253 offset:23552
	global_load_lds_dwordx4 v158, s[100:101]
	s_waitcnt vmcnt(10)
	s_barrier
	s_waitcnt lgkmcnt(0)
	v_mfma_f32_16x16x32_bf16 v[62:65], v[130:133], v[146:149], 0
	v_mfma_f32_16x16x32_bf16 v[10:13], v[138:141], v[146:149], 0
	v_mfma_f32_16x16x32_bf16 v[58:61], v[130:133], v[168:171], 0
	v_mfma_f32_16x16x32_bf16 v[14:17], v[138:141], v[168:171], 0
	v_mfma_f32_16x16x32_bf16 v[54:57], v[130:133], v[176:179], 0
	v_mfma_f32_16x16x32_bf16 v[6:9], v[138:141], v[176:179], 0
	v_mfma_f32_16x16x32_bf16 v[42:45], v[130:133], v[184:187], 0
	v_mfma_f32_16x16x32_bf16 v[2:5], v[138:141], v[184:187], 0
	v_mfma_f32_16x16x32_bf16 v[62:65], v[134:137], v[150:153], v[62:65]
	v_mfma_f32_16x16x32_bf16 v[10:13], v[142:145], v[150:153], v[10:13]
	v_mfma_f32_16x16x32_bf16 v[58:61], v[134:137], v[172:175], v[58:61]
	v_mfma_f32_16x16x32_bf16 v[14:17], v[142:145], v[172:175], v[14:17]
	v_mfma_f32_16x16x32_bf16 v[54:57], v[134:137], v[180:183], v[54:57]
	v_mfma_f32_16x16x32_bf16 v[6:9], v[142:145], v[180:183], v[6:9]
	v_mfma_f32_16x16x32_bf16 v[42:45], v[134:137], v[190:193], v[42:45]
	v_mfma_f32_16x16x32_bf16 v[2:5], v[142:145], v[190:193], v[2:5]
	s_barrier
	s_add_u32 s6, s90, 0x40000
	s_addc_u32 s7, s91, 0
	s_add_i32 m0, s39, 0x14000
	s_nop 0
	global_load_lds_dwordx4 v160, s[6:7]
	s_add_i32 m0, s39, 0x16000
	s_nop 0
	global_load_lds_dwordx4 v156, s[6:7]
	ds_read_b128 v[130:133], v189 offset:32768
	ds_read_b128 v[134:137], v189 offset:33792
	ds_read_b128 v[138:141], v189 offset:34816
	ds_read_b128 v[142:145], v189 offset:35840
	s_waitcnt vmcnt(6)
	s_barrier
	v_mfma_f32_16x16x32_bf16 v[50:53], v[194:197], v[146:149], 0
	v_mfma_f32_16x16x32_bf16 v[26:29], v[202:205], v[146:149], 0
	v_mfma_f32_16x16x32_bf16 v[46:49], v[194:197], v[168:171], 0
	v_mfma_f32_16x16x32_bf16 v[30:33], v[202:205], v[168:171], 0
	v_mfma_f32_16x16x32_bf16 v[38:41], v[194:197], v[176:179], 0
	v_mfma_f32_16x16x32_bf16 v[22:25], v[202:205], v[176:179], 0
	v_mfma_f32_16x16x32_bf16 v[34:37], v[194:197], v[184:187], 0
	v_mfma_f32_16x16x32_bf16 v[18:21], v[202:205], v[184:187], 0
	v_mfma_f32_16x16x32_bf16 v[50:53], v[198:201], v[150:153], v[50:53]
	v_mfma_f32_16x16x32_bf16 v[26:29], v[206:209], v[150:153], v[26:29]
	v_mfma_f32_16x16x32_bf16 v[46:49], v[198:201], v[172:175], v[46:49]
	v_mfma_f32_16x16x32_bf16 v[30:33], v[206:209], v[172:175], v[30:33]
	v_mfma_f32_16x16x32_bf16 v[38:41], v[198:201], v[180:183], v[38:41]
	v_mfma_f32_16x16x32_bf16 v[22:25], v[206:209], v[180:183], v[22:25]
	v_mfma_f32_16x16x32_bf16 v[34:37], v[198:201], v[190:193], v[34:37]
	v_mfma_f32_16x16x32_bf16 v[18:21], v[206:209], v[190:193], v[18:21]
	s_barrier
	s_add_u32 s6, s92, 0x40000
	s_addc_u32 s7, s93, 0
	s_mov_b32 m0, s61
	ds_read_b128 v[146:149], v253 offset:32768
	ds_read_b128 v[150:153], v253 offset:33792
	ds_read_b128 v[168:171], v253 offset:34816
	ds_read_b128 v[172:175], v253 offset:35840
	ds_read_b128 v[176:179], v253 offset:36864
	ds_read_b128 v[180:183], v253 offset:37888
	ds_read_b128 v[184:187], v253 offset:38912
	global_load_lds_dwordx4 v162, s[6:7]
	s_mov_b32 m0, s72
	ds_read_b128 v[190:193], v253 offset:39936
	global_load_lds_dwordx4 v158, s[6:7]
	s_waitcnt lgkmcnt(8)
	s_barrier
	s_waitcnt lgkmcnt(0)
	v_mfma_f32_16x16x32_bf16 v[126:129], v[130:133], v[146:149], v[126:129]
	v_mfma_f32_16x16x32_bf16 v[70:73], v[138:141], v[146:149], v[70:73]
	v_mfma_f32_16x16x32_bf16 v[122:125], v[130:133], v[168:171], v[122:125]
	v_mfma_f32_16x16x32_bf16 v[74:77], v[138:141], v[168:171], v[74:77]
	v_mfma_f32_16x16x32_bf16 v[114:117], v[130:133], v[176:179], v[114:117]
	v_mfma_f32_16x16x32_bf16 v[66:69], v[138:141], v[176:179], v[66:69]
	v_mfma_f32_16x16x32_bf16 v[110:113], v[130:133], v[184:187], v[110:113]
	v_mfma_f32_16x16x32_bf16 v[78:81], v[138:141], v[184:187], v[78:81]
	v_mfma_f32_16x16x32_bf16 v[126:129], v[134:137], v[150:153], v[126:129]
	v_mfma_f32_16x16x32_bf16 v[70:73], v[142:145], v[150:153], v[70:73]
	v_mfma_f32_16x16x32_bf16 v[122:125], v[134:137], v[172:175], v[122:125]
	v_mfma_f32_16x16x32_bf16 v[74:77], v[142:145], v[172:175], v[74:77]
	v_mfma_f32_16x16x32_bf16 v[114:117], v[134:137], v[180:183], v[114:117]
	v_mfma_f32_16x16x32_bf16 v[66:69], v[142:145], v[180:183], v[66:69]
	v_mfma_f32_16x16x32_bf16 v[110:113], v[134:137], v[190:193], v[110:113]
	v_mfma_f32_16x16x32_bf16 v[78:81], v[142:145], v[190:193], v[78:81]
	s_barrier
	s_add_i32 m0, s39, 0x18000
	ds_read_b128 v[194:197], v189 offset:49152
	ds_read_b128 v[198:201], v189 offset:50176
	ds_read_b128 v[202:205], v189 offset:51200
	ds_read_b128 v[206:209], v189 offset:52224
	s_add_u32 s98, s90, s40
	s_addc_u32 s99, s91, s41
	global_load_lds_dwordx4 v160, s[98:99]
	s_add_i32 m0, s39, 0x1a000
	s_nop 0
	global_load_lds_dwordx4 v156, s[98:99]
	s_barrier
	s_waitcnt lgkmcnt(0)
	v_mfma_f32_16x16x32_bf16 v[118:121], v[194:197], v[146:149], v[118:121]
	v_mfma_f32_16x16x32_bf16 v[94:97], v[202:205], v[146:149], v[94:97]
	v_mfma_f32_16x16x32_bf16 v[106:109], v[194:197], v[168:171], v[106:109]
	v_mfma_f32_16x16x32_bf16 v[90:93], v[202:205], v[168:171], v[90:93]
	v_mfma_f32_16x16x32_bf16 v[102:105], v[194:197], v[176:179], v[102:105]
	v_mfma_f32_16x16x32_bf16 v[82:85], v[202:205], v[176:179], v[82:85]
	v_mfma_f32_16x16x32_bf16 v[98:101], v[194:197], v[184:187], v[98:101]
	v_mfma_f32_16x16x32_bf16 v[86:89], v[202:205], v[184:187], v[86:89]
	v_mfma_f32_16x16x32_bf16 v[118:121], v[198:201], v[150:153], v[118:121]
	v_mfma_f32_16x16x32_bf16 v[94:97], v[206:209], v[150:153], v[94:97]
	v_mfma_f32_16x16x32_bf16 v[106:109], v[198:201], v[172:175], v[106:109]
	v_mfma_f32_16x16x32_bf16 v[90:93], v[206:209], v[172:175], v[90:93]
	v_mfma_f32_16x16x32_bf16 v[102:105], v[198:201], v[180:183], v[102:105]
	v_mfma_f32_16x16x32_bf16 v[82:85], v[206:209], v[180:183], v[82:85]
	v_mfma_f32_16x16x32_bf16 v[98:101], v[198:201], v[190:193], v[98:101]
	v_mfma_f32_16x16x32_bf16 v[86:89], v[206:209], v[190:193], v[86:89]
	s_mov_b32 m0, s95
	s_barrier
	ds_read_b128 v[146:149], v253 offset:49152
	ds_read_b128 v[150:153], v253 offset:50176
	ds_read_b128 v[168:171], v253 offset:51200
	ds_read_b128 v[172:175], v253 offset:52224
	ds_read_b128 v[176:179], v253 offset:53248
	ds_read_b128 v[180:183], v253 offset:54272
	ds_read_b128 v[184:187], v253 offset:55296
	ds_read_b128 v[190:193], v253 offset:56320
	s_add_u32 s98, s100, s40
	s_addc_u32 s99, s101, s41
	global_load_lds_dwordx4 v162, s[98:99]
	s_mov_b32 m0, s96
	s_nop 0
	global_load_lds_dwordx4 v158, s[98:99]
	s_waitcnt vmcnt(10)
	s_barrier
	s_waitcnt lgkmcnt(0)
	v_mfma_f32_16x16x32_bf16 v[62:65], v[130:133], v[146:149], v[62:65]
	v_mfma_f32_16x16x32_bf16 v[10:13], v[138:141], v[146:149], v[10:13]
	v_mfma_f32_16x16x32_bf16 v[58:61], v[130:133], v[168:171], v[58:61]
	v_mfma_f32_16x16x32_bf16 v[14:17], v[138:141], v[168:171], v[14:17]
	v_mfma_f32_16x16x32_bf16 v[54:57], v[130:133], v[176:179], v[54:57]
	v_mfma_f32_16x16x32_bf16 v[6:9], v[138:141], v[176:179], v[6:9]
	v_mfma_f32_16x16x32_bf16 v[42:45], v[130:133], v[184:187], v[42:45]
	v_mfma_f32_16x16x32_bf16 v[2:5], v[138:141], v[184:187], v[2:5]
	v_mfma_f32_16x16x32_bf16 v[62:65], v[134:137], v[150:153], v[62:65]
	v_mfma_f32_16x16x32_bf16 v[10:13], v[142:145], v[150:153], v[10:13]
	v_mfma_f32_16x16x32_bf16 v[58:61], v[134:137], v[172:175], v[58:61]
	v_mfma_f32_16x16x32_bf16 v[14:17], v[142:145], v[172:175], v[14:17]
	v_mfma_f32_16x16x32_bf16 v[54:57], v[134:137], v[180:183], v[54:57]
	v_mfma_f32_16x16x32_bf16 v[6:9], v[142:145], v[180:183], v[6:9]
	v_mfma_f32_16x16x32_bf16 v[42:45], v[134:137], v[190:193], v[42:45]
	v_mfma_f32_16x16x32_bf16 v[2:5], v[142:145], v[190:193], v[2:5]
	s_barrier
	s_add_u32 s6, s90, 0x40080
	s_addc_u32 s7, s91, 0
	s_add_i32 m0, s39, 0x1c000
	s_nop 0
	global_load_lds_dwordx4 v160, s[6:7]
	s_add_i32 m0, s39, 0x1e000
	s_nop 0
	global_load_lds_dwordx4 v156, s[6:7]
	ds_read_b128 v[130:133], v189
	ds_read_b128 v[134:137], v189 offset:1024
	ds_read_b128 v[138:141], v189 offset:2048
	ds_read_b128 v[142:145], v189 offset:3072
	s_waitcnt vmcnt(6)
	s_barrier
	v_mfma_f32_16x16x32_bf16 v[50:53], v[194:197], v[146:149], v[50:53]
	v_mfma_f32_16x16x32_bf16 v[26:29], v[202:205], v[146:149], v[26:29]
	v_mfma_f32_16x16x32_bf16 v[46:49], v[194:197], v[168:171], v[46:49]
	v_mfma_f32_16x16x32_bf16 v[30:33], v[202:205], v[168:171], v[30:33]
	v_mfma_f32_16x16x32_bf16 v[38:41], v[194:197], v[176:179], v[38:41]
	v_mfma_f32_16x16x32_bf16 v[22:25], v[202:205], v[176:179], v[22:25]
	v_mfma_f32_16x16x32_bf16 v[34:37], v[194:197], v[184:187], v[34:37]
	v_mfma_f32_16x16x32_bf16 v[18:21], v[202:205], v[184:187], v[18:21]
	v_mfma_f32_16x16x32_bf16 v[50:53], v[198:201], v[150:153], v[50:53]
	v_mfma_f32_16x16x32_bf16 v[26:29], v[206:209], v[150:153], v[26:29]
	v_mfma_f32_16x16x32_bf16 v[46:49], v[198:201], v[172:175], v[46:49]
	v_mfma_f32_16x16x32_bf16 v[30:33], v[206:209], v[172:175], v[30:33]
	v_mfma_f32_16x16x32_bf16 v[38:41], v[198:201], v[180:183], v[38:41]
	v_mfma_f32_16x16x32_bf16 v[22:25], v[206:209], v[180:183], v[22:25]
	v_mfma_f32_16x16x32_bf16 v[34:37], v[198:201], v[190:193], v[34:37]
	v_mfma_f32_16x16x32_bf16 v[18:21], v[206:209], v[190:193], v[18:21]
	s_add_i32 s45, s45, 2
	s_add_u32 s28, s28, 0x100
	s_addc_u32 s29, s29, 0
	s_mov_b64 s[6:7], s[88:89]
	s_add_u32 s88, s6, 0x100
	s_addc_u32 s89, s7, 0
	s_cmp_eq_u32 s45, 12
	s_cselect_b32 s93, s17, s89
	s_cselect_b32 s92, s22, s88
	s_cselect_b32 s91, s15, s29
	s_cselect_b32 s90, s23, s28
	s_cmp_gt_u32 s45, 13
	s_barrier
	.p2align 6
	s_nop 0
	s_nop 0
	s_nop 0
	s_nop 0
	s_nop 0
	s_nop 0
	s_nop 0
	s_nop 0

.LBB0_1089:
	s_add_u32 s34, s84, 0x100
	s_addc_u32 s78, s85, 0
	s_mov_b32 s79, -2
	s_waitcnt lgkmcnt(0)
	s_add_i32 s90, 0, 0x10000
	v_add_u32_e32 v142, s90, v212
	v_add_u32_e32 v189, 0x10000, v212
	ds_read_b128 v[130:133], v142
	ds_read_b128 v[134:137], v142 offset:1024
	ds_read_b128 v[138:141], v142 offset:2048
	ds_read_b128 v[142:145], v142 offset:3072
	s_add_u32 s84, s16, 0x100
	s_addc_u32 s85, s17, 0
	s_cmp_eq_u32 s79, 40
	s_cselect_b32 s89, s5, s85
	s_cselect_b32 s88, s4, s84
	s_cselect_b32 s87, s7, s78
	s_cselect_b32 s86, s6, s34
	v_lshl_add_u64 v[178:179], s[16:17], 0, v[196:197]
	s_add_i32 m0, s39, 0xc000
	ds_read_b128 v[146:149], v213
	ds_read_b128 v[150:153], v213 offset:1024
	ds_read_b128 v[154:157], v213 offset:2048
	ds_read_b128 v[158:161], v213 offset:3072
	ds_read_b128 v[162:165], v213 offset:4096
	ds_read_b128 v[166:169], v213 offset:5120
	ds_read_b128 v[170:173], v213 offset:6144
	ds_read_b128 v[174:177], v213 offset:7168
	global_load_lds_dwordx4 v[178:179], off
	s_add_i32 m0, s39, 0xe000
	v_lshl_add_u64 v[178:179], s[16:17], 0, v[198:199]
	global_load_lds_dwordx4 v[178:179], off
	s_waitcnt lgkmcnt(8)
	s_barrier
	s_waitcnt lgkmcnt(0)
	v_mfma_f32_16x16x32_bf16 v[126:129], v[130:133], v[146:149], 0
	v_mfma_f32_16x16x32_bf16 v[122:125], v[138:141], v[146:149], 0
	v_mfma_f32_16x16x32_bf16 v[110:113], v[130:133], v[154:157], 0
	v_mfma_f32_16x16x32_bf16 v[106:109], v[138:141], v[154:157], 0
	v_mfma_f32_16x16x32_bf16 v[94:97], v[130:133], v[162:165], 0
	v_mfma_f32_16x16x32_bf16 v[90:93], v[138:141], v[162:165], 0
	v_mfma_f32_16x16x32_bf16 v[78:81], v[130:133], v[170:173], 0
	v_mfma_f32_16x16x32_bf16 v[74:77], v[138:141], v[170:173], 0
	v_mfma_f32_16x16x32_bf16 v[126:129], v[134:137], v[150:153], v[126:129]
	v_mfma_f32_16x16x32_bf16 v[122:125], v[142:145], v[150:153], v[122:125]
	v_mfma_f32_16x16x32_bf16 v[110:113], v[134:137], v[158:161], v[110:113]
	v_mfma_f32_16x16x32_bf16 v[106:109], v[142:145], v[158:161], v[106:109]
	v_mfma_f32_16x16x32_bf16 v[94:97], v[134:137], v[166:169], v[94:97]
	v_mfma_f32_16x16x32_bf16 v[90:93], v[142:145], v[166:169], v[90:93]
	v_mfma_f32_16x16x32_bf16 v[78:81], v[134:137], v[174:177], v[78:81]
	v_mfma_f32_16x16x32_bf16 v[74:77], v[142:145], v[174:177], v[74:77]
	s_barrier
	ds_read_b128 v[178:181], v189 offset:16384
	ds_read_b128 v[182:185], v189 offset:17408
	ds_read_b128 v[200:203], v189 offset:18432
	ds_read_b128 v[204:207], v189 offset:19456
	s_add_i32 m0, s38, 0x10000
	s_nop 0
	global_load_lds_dwordx4 v0, s[86:87]
	s_add_i32 m0, s38, 0x12000
	s_nop 0
	global_load_lds_dwordx4 v194, s[86:87]
	s_barrier
	s_waitcnt lgkmcnt(0)
	v_mfma_f32_16x16x32_bf16 v[118:121], v[178:181], v[146:149], 0
	v_mfma_f32_16x16x32_bf16 v[114:117], v[200:203], v[146:149], 0
	v_mfma_f32_16x16x32_bf16 v[102:105], v[178:181], v[154:157], 0
	v_mfma_f32_16x16x32_bf16 v[98:101], v[200:203], v[154:157], 0
	v_mfma_f32_16x16x32_bf16 v[86:89], v[178:181], v[162:165], 0
	v_mfma_f32_16x16x32_bf16 v[82:85], v[200:203], v[162:165], 0
	v_mfma_f32_16x16x32_bf16 v[70:73], v[178:181], v[170:173], 0
	v_mfma_f32_16x16x32_bf16 v[66:69], v[200:203], v[170:173], 0
	v_mfma_f32_16x16x32_bf16 v[118:121], v[182:185], v[150:153], v[118:121]
	v_mfma_f32_16x16x32_bf16 v[114:117], v[204:207], v[150:153], v[114:117]
	v_mfma_f32_16x16x32_bf16 v[102:105], v[182:185], v[158:161], v[102:105]
	v_mfma_f32_16x16x32_bf16 v[98:101], v[204:207], v[158:161], v[98:101]
	v_mfma_f32_16x16x32_bf16 v[86:89], v[182:185], v[166:169], v[86:89]
	v_mfma_f32_16x16x32_bf16 v[82:85], v[204:207], v[166:169], v[82:85]
	v_mfma_f32_16x16x32_bf16 v[70:73], v[182:185], v[174:177], v[70:73]
	v_mfma_f32_16x16x32_bf16 v[66:69], v[204:207], v[174:177], v[66:69]
	s_mov_b32 m0, s39
	s_mov_b64 s[100:101], s[88:89]
	s_barrier
	ds_read_b128 v[146:149], v213 offset:16384
	ds_read_b128 v[150:153], v213 offset:17408
	ds_read_b128 v[154:157], v213 offset:18432
	ds_read_b128 v[158:161], v213 offset:19456
	ds_read_b128 v[162:165], v213 offset:20480
	ds_read_b128 v[166:169], v213 offset:21504
	ds_read_b128 v[170:173], v213 offset:22528
	global_load_lds_dwordx4 v190, s[100:101]
	s_mov_b32 m0, s42
	ds_read_b128 v[174:177], v213 offset:23552
	global_load_lds_dwordx4 v192, s[100:101]
	s_waitcnt vmcnt(10)
	s_barrier
	s_waitcnt lgkmcnt(0)
	v_mfma_f32_16x16x32_bf16 v[62:65], v[130:133], v[146:149], 0
	v_mfma_f32_16x16x32_bf16 v[58:61], v[138:141], v[146:149], 0
	v_mfma_f32_16x16x32_bf16 v[46:49], v[130:133], v[154:157], 0
	v_mfma_f32_16x16x32_bf16 v[42:45], v[138:141], v[154:157], 0
	v_mfma_f32_16x16x32_bf16 v[30:33], v[130:133], v[162:165], 0
	v_mfma_f32_16x16x32_bf16 v[26:29], v[138:141], v[162:165], 0
	v_mfma_f32_16x16x32_bf16 v[14:17], v[130:133], v[170:173], 0
	v_mfma_f32_16x16x32_bf16 v[10:13], v[138:141], v[170:173], 0
	v_mfma_f32_16x16x32_bf16 v[62:65], v[134:137], v[150:153], v[62:65]
	v_mfma_f32_16x16x32_bf16 v[58:61], v[142:145], v[150:153], v[58:61]
	v_mfma_f32_16x16x32_bf16 v[46:49], v[134:137], v[158:161], v[46:49]
	v_mfma_f32_16x16x32_bf16 v[42:45], v[142:145], v[158:161], v[42:45]
	v_mfma_f32_16x16x32_bf16 v[30:33], v[134:137], v[166:169], v[30:33]
	v_mfma_f32_16x16x32_bf16 v[26:29], v[142:145], v[166:169], v[26:29]
	v_mfma_f32_16x16x32_bf16 v[14:17], v[134:137], v[174:177], v[14:17]
	v_mfma_f32_16x16x32_bf16 v[10:13], v[142:145], v[174:177], v[10:13]
	s_barrier
	s_add_u32 s16, s86, 0xb0000
	s_addc_u32 s17, s87, 0
	s_add_i32 m0, s38, 0x14000
	s_nop 0
	global_load_lds_dwordx4 v0, s[16:17]
	s_add_i32 m0, s38, 0x16000
	s_nop 0
	global_load_lds_dwordx4 v194, s[16:17]
	s_add_i32 s90, 0, 0x18000
	v_add_u32_e32 v142, s90, v212
	ds_read_b128 v[130:133], v142
	ds_read_b128 v[134:137], v142 offset:1024
	ds_read_b128 v[138:141], v142 offset:2048
	ds_read_b128 v[142:145], v142 offset:3072
	s_waitcnt vmcnt(6)
	s_barrier
	v_mfma_f32_16x16x32_bf16 v[54:57], v[178:181], v[146:149], 0
	v_mfma_f32_16x16x32_bf16 v[50:53], v[200:203], v[146:149], 0
	v_mfma_f32_16x16x32_bf16 v[38:41], v[178:181], v[154:157], 0
	v_mfma_f32_16x16x32_bf16 v[34:37], v[200:203], v[154:157], 0
	v_mfma_f32_16x16x32_bf16 v[22:25], v[178:181], v[162:165], 0
	v_mfma_f32_16x16x32_bf16 v[18:21], v[200:203], v[162:165], 0
	v_mfma_f32_16x16x32_bf16 v[6:9], v[178:181], v[170:173], 0
	v_mfma_f32_16x16x32_bf16 v[2:5], v[200:203], v[170:173], 0
	v_mfma_f32_16x16x32_bf16 v[54:57], v[182:185], v[150:153], v[54:57]
	v_mfma_f32_16x16x32_bf16 v[50:53], v[204:207], v[150:153], v[50:53]
	v_mfma_f32_16x16x32_bf16 v[38:41], v[182:185], v[158:161], v[38:41]
	v_mfma_f32_16x16x32_bf16 v[34:37], v[204:207], v[158:161], v[34:37]
	v_mfma_f32_16x16x32_bf16 v[22:25], v[182:185], v[166:169], v[22:25]
	v_mfma_f32_16x16x32_bf16 v[18:21], v[204:207], v[166:169], v[18:21]
	v_mfma_f32_16x16x32_bf16 v[6:9], v[182:185], v[174:177], v[6:9]
	v_mfma_f32_16x16x32_bf16 v[2:5], v[204:207], v[174:177], v[2:5]
	s_barrier
	s_add_u32 s16, s88, 0xb0000
	s_addc_u32 s17, s89, 0
	s_mov_b32 m0, s43
	ds_read_b128 v[146:149], v213 offset:32768
	ds_read_b128 v[150:153], v213 offset:33792
	ds_read_b128 v[154:157], v213 offset:34816
	ds_read_b128 v[158:161], v213 offset:35840
	ds_read_b128 v[162:165], v213 offset:36864
	ds_read_b128 v[166:169], v213 offset:37888
	ds_read_b128 v[170:173], v213 offset:38912
	global_load_lds_dwordx4 v190, s[16:17]
	s_mov_b32 m0, s44
	ds_read_b128 v[174:177], v213 offset:39936
	global_load_lds_dwordx4 v192, s[16:17]
	s_waitcnt lgkmcnt(8)
	s_barrier
	s_waitcnt lgkmcnt(0)
	v_mfma_f32_16x16x32_bf16 v[126:129], v[130:133], v[146:149], v[126:129]
	v_mfma_f32_16x16x32_bf16 v[122:125], v[138:141], v[146:149], v[122:125]
	v_mfma_f32_16x16x32_bf16 v[110:113], v[130:133], v[154:157], v[110:113]
	v_mfma_f32_16x16x32_bf16 v[106:109], v[138:141], v[154:157], v[106:109]
	v_mfma_f32_16x16x32_bf16 v[94:97], v[130:133], v[162:165], v[94:97]
	v_mfma_f32_16x16x32_bf16 v[90:93], v[138:141], v[162:165], v[90:93]
	v_mfma_f32_16x16x32_bf16 v[78:81], v[130:133], v[170:173], v[78:81]
	v_mfma_f32_16x16x32_bf16 v[74:77], v[138:141], v[170:173], v[74:77]
	v_mfma_f32_16x16x32_bf16 v[126:129], v[134:137], v[150:153], v[126:129]
	v_mfma_f32_16x16x32_bf16 v[122:125], v[142:145], v[150:153], v[122:125]
	v_mfma_f32_16x16x32_bf16 v[110:113], v[134:137], v[158:161], v[110:113]
	v_mfma_f32_16x16x32_bf16 v[106:109], v[142:145], v[158:161], v[106:109]
	v_mfma_f32_16x16x32_bf16 v[94:97], v[134:137], v[166:169], v[94:97]
	v_mfma_f32_16x16x32_bf16 v[90:93], v[142:145], v[166:169], v[90:93]
	v_mfma_f32_16x16x32_bf16 v[78:81], v[134:137], v[174:177], v[78:81]
	v_mfma_f32_16x16x32_bf16 v[74:77], v[142:145], v[174:177], v[74:77]
	s_barrier
	s_add_i32 s88, 0, 0x1c000
	v_add_u32_e32 v204, s88, v212
	s_add_i32 m0, s38, 0x18000
	ds_read_b128 v[178:181], v204
	ds_read_b128 v[182:185], v204 offset:1024
	ds_read_b128 v[200:203], v204 offset:2048
	ds_read_b128 v[204:207], v204 offset:3072
	s_add_u32 s98, s86, s40
	s_addc_u32 s99, s87, s41
	global_load_lds_dwordx4 v0, s[98:99]
	s_add_i32 m0, s38, 0x1a000
	s_nop 0
	global_load_lds_dwordx4 v194, s[98:99]
	s_barrier
	s_waitcnt lgkmcnt(0)
	v_mfma_f32_16x16x32_bf16 v[118:121], v[178:181], v[146:149], v[118:121]
	v_mfma_f32_16x16x32_bf16 v[114:117], v[200:203], v[146:149], v[114:117]
	v_mfma_f32_16x16x32_bf16 v[102:105], v[178:181], v[154:157], v[102:105]
	v_mfma_f32_16x16x32_bf16 v[98:101], v[200:203], v[154:157], v[98:101]
	v_mfma_f32_16x16x32_bf16 v[86:89], v[178:181], v[162:165], v[86:89]
	v_mfma_f32_16x16x32_bf16 v[82:85], v[200:203], v[162:165], v[82:85]
	v_mfma_f32_16x16x32_bf16 v[70:73], v[178:181], v[170:173], v[70:73]
	v_mfma_f32_16x16x32_bf16 v[66:69], v[200:203], v[170:173], v[66:69]
	v_mfma_f32_16x16x32_bf16 v[118:121], v[182:185], v[150:153], v[118:121]
	v_mfma_f32_16x16x32_bf16 v[114:117], v[204:207], v[150:153], v[114:117]
	v_mfma_f32_16x16x32_bf16 v[102:105], v[182:185], v[158:161], v[102:105]
	v_mfma_f32_16x16x32_bf16 v[98:101], v[204:207], v[158:161], v[98:101]
	v_mfma_f32_16x16x32_bf16 v[86:89], v[182:185], v[166:169], v[86:89]
	v_mfma_f32_16x16x32_bf16 v[82:85], v[204:207], v[166:169], v[82:85]
	v_mfma_f32_16x16x32_bf16 v[70:73], v[182:185], v[174:177], v[70:73]
	v_mfma_f32_16x16x32_bf16 v[66:69], v[204:207], v[174:177], v[66:69]
	s_mov_b32 m0, s60
	s_barrier
	ds_read_b128 v[146:149], v213 offset:49152
	ds_read_b128 v[150:153], v213 offset:50176
	ds_read_b128 v[154:157], v213 offset:51200
	ds_read_b128 v[158:161], v213 offset:52224
	ds_read_b128 v[162:165], v213 offset:53248
	ds_read_b128 v[166:169], v213 offset:54272
	ds_read_b128 v[170:173], v213 offset:55296
	ds_read_b128 v[174:177], v213 offset:56320
	s_add_u32 s98, s100, s40
	s_addc_u32 s99, s101, s41
	global_load_lds_dwordx4 v190, s[98:99]
	s_mov_b32 m0, s61
	s_nop 0
	global_load_lds_dwordx4 v192, s[98:99]
	s_waitcnt vmcnt(10)
	s_barrier
	s_waitcnt lgkmcnt(0)
	v_mfma_f32_16x16x32_bf16 v[62:65], v[130:133], v[146:149], v[62:65]
	v_mfma_f32_16x16x32_bf16 v[58:61], v[138:141], v[146:149], v[58:61]
	v_mfma_f32_16x16x32_bf16 v[46:49], v[130:133], v[154:157], v[46:49]
	v_mfma_f32_16x16x32_bf16 v[42:45], v[138:141], v[154:157], v[42:45]
	v_mfma_f32_16x16x32_bf16 v[30:33], v[130:133], v[162:165], v[30:33]
	v_mfma_f32_16x16x32_bf16 v[26:29], v[138:141], v[162:165], v[26:29]
	v_mfma_f32_16x16x32_bf16 v[14:17], v[130:133], v[170:173], v[14:17]
	v_mfma_f32_16x16x32_bf16 v[10:13], v[138:141], v[170:173], v[10:13]
	v_mfma_f32_16x16x32_bf16 v[62:65], v[134:137], v[150:153], v[62:65]
	v_mfma_f32_16x16x32_bf16 v[58:61], v[142:145], v[150:153], v[58:61]
	v_mfma_f32_16x16x32_bf16 v[46:49], v[134:137], v[158:161], v[46:49]
	v_mfma_f32_16x16x32_bf16 v[42:45], v[142:145], v[158:161], v[42:45]
	v_mfma_f32_16x16x32_bf16 v[30:33], v[134:137], v[166:169], v[30:33]
	v_mfma_f32_16x16x32_bf16 v[26:29], v[142:145], v[166:169], v[26:29]
	v_mfma_f32_16x16x32_bf16 v[14:17], v[134:137], v[174:177], v[14:17]
	v_mfma_f32_16x16x32_bf16 v[10:13], v[142:145], v[174:177], v[10:13]
	s_barrier
	s_add_u32 s16, s86, 0xb0080
	s_addc_u32 s17, s87, 0
	s_add_i32 m0, s38, 0x1c000
	s_nop 0
	global_load_lds_dwordx4 v0, s[16:17]
	s_add_i32 m0, s38, 0x1e000
	s_nop 0
	global_load_lds_dwordx4 v194, s[16:17]
	ds_read_b128 v[130:133], v189
	ds_read_b128 v[134:137], v189 offset:1024
	ds_read_b128 v[138:141], v189 offset:2048
	ds_read_b128 v[142:145], v189 offset:3072
	s_waitcnt vmcnt(6)
	s_barrier
	v_mfma_f32_16x16x32_bf16 v[54:57], v[178:181], v[146:149], v[54:57]
	v_mfma_f32_16x16x32_bf16 v[50:53], v[200:203], v[146:149], v[50:53]
	v_mfma_f32_16x16x32_bf16 v[38:41], v[178:181], v[154:157], v[38:41]
	v_mfma_f32_16x16x32_bf16 v[34:37], v[200:203], v[154:157], v[34:37]
	v_mfma_f32_16x16x32_bf16 v[22:25], v[178:181], v[162:165], v[22:25]
	v_mfma_f32_16x16x32_bf16 v[18:21], v[200:203], v[162:165], v[18:21]
	v_mfma_f32_16x16x32_bf16 v[6:9], v[178:181], v[170:173], v[6:9]
	v_mfma_f32_16x16x32_bf16 v[2:5], v[200:203], v[170:173], v[2:5]
	v_mfma_f32_16x16x32_bf16 v[54:57], v[182:185], v[150:153], v[54:57]
	v_mfma_f32_16x16x32_bf16 v[50:53], v[204:207], v[150:153], v[50:53]
	v_mfma_f32_16x16x32_bf16 v[38:41], v[182:185], v[158:161], v[38:41]
	v_mfma_f32_16x16x32_bf16 v[34:37], v[204:207], v[158:161], v[34:37]
	v_mfma_f32_16x16x32_bf16 v[22:25], v[182:185], v[166:169], v[22:25]
	v_mfma_f32_16x16x32_bf16 v[18:21], v[204:207], v[166:169], v[18:21]
	v_mfma_f32_16x16x32_bf16 v[6:9], v[182:185], v[174:177], v[6:9]
	v_mfma_f32_16x16x32_bf16 v[2:5], v[204:207], v[174:177], v[2:5]
	s_add_i32 s79, s79, 2
	s_add_u32 s34, s34, 0x100
	s_addc_u32 s78, s78, 0
	s_mov_b64 s[16:17], s[84:85]
	s_add_u32 s84, s16, 0x100
	s_addc_u32 s85, s17, 0
	s_cmp_eq_u32 s79, 40
	s_cselect_b32 s89, s5, s85
	s_cselect_b32 s88, s4, s84
	s_cselect_b32 s87, s7, s78
	s_cselect_b32 s86, s6, s34
	s_cmp_gt_u32 s79, 41
	s_barrier
	.p2align 6
	s_nop 0
	s_nop 0
	s_nop 0
	s_nop 0
	s_nop 0
	s_nop 0
	s_nop 0
	s_nop 0

.LBB0_1208:
	s_ashr_i32 s13, s12, 31
	v_cmp_lt_i64_e32 vcc, s[14:15], v[230:231]
	s_lshl_b64 s[14:15], s[12:13], 19
	s_add_u32 s14, s80, s14
	s_addc_u32 s15, s81, s15
	s_and_b64 s[16:17], vcc, exec
	s_cselect_b32 s13, s15, s89
	s_cselect_b32 s22, s14, s88
	s_ashr_i32 s7, s6, 31
	s_lshl_b64 s[16:17], s[6:7], 19
	s_add_u32 s16, s36, s16
	s_addc_u32 s17, s37, s17
	s_and_b64 s[92:93], vcc, exec
	s_cselect_b32 s7, s17, s91
	s_cselect_b32 s23, s16, s90
	s_add_u32 s88, s88, 0x40080
	s_addc_u32 s89, s89, 0
	s_add_u32 s34, s90, 0x100
	s_addc_u32 s79, s91, 0
	s_mov_b32 s85, -2
	s_waitcnt lgkmcnt(0)
	s_add_i32 s94, 0, 0x10000
	v_add_u32_e32 v0, s94, v170
	v_add_u32_e32 v189, 0x10000, v170
	ds_read_b128 v[130:133], v0
	ds_read_b128 v[134:137], v0 offset:1024
	ds_read_b128 v[138:141], v0 offset:2048
	ds_read_b128 v[142:145], v0 offset:3072
	s_add_u32 s87, s88, 0xfffc0080
	s_addc_u32 s90, s89, -1
	s_cmp_eq_u32 s85, 12
	s_cselect_b32 s93, s13, s90
	s_cselect_b32 s92, s22, s87
	s_cselect_b32 s91, s7, s79
	s_cselect_b32 s90, s23, s34
	s_waitcnt lgkmcnt(0)
	s_add_i32 m0, s39, 0xc000
	ds_read_b128 v[158:161], v171
	ds_read_b128 v[162:165], v171 offset:1024
	ds_read_b128 v[166:169], v171 offset:2048
	ds_read_b128 v[172:175], v171 offset:3072
	ds_read_b128 v[176:179], v171 offset:4096
	ds_read_b128 v[180:183], v171 offset:5120
	ds_read_b128 v[184:187], v171 offset:6144
	global_load_lds_dwordx4 v154, s[88:89]
	s_add_i32 m0, s39, 0xe000
	ds_read_b128 v[190:193], v171 offset:7168
	global_load_lds_dwordx4 v156, s[88:89]
	s_waitcnt lgkmcnt(8)
	s_barrier
	s_waitcnt lgkmcnt(0)
	v_mfma_f32_16x16x32_bf16 v[126:129], v[130:133], v[158:161], 0
	v_mfma_f32_16x16x32_bf16 v[122:125], v[138:141], v[158:161], 0
	v_mfma_f32_16x16x32_bf16 v[110:113], v[130:133], v[166:169], 0
	v_mfma_f32_16x16x32_bf16 v[106:109], v[138:141], v[166:169], 0
	v_mfma_f32_16x16x32_bf16 v[94:97], v[130:133], v[176:179], 0
	v_mfma_f32_16x16x32_bf16 v[90:93], v[138:141], v[176:179], 0
	v_mfma_f32_16x16x32_bf16 v[78:81], v[130:133], v[184:187], 0
	v_mfma_f32_16x16x32_bf16 v[74:77], v[138:141], v[184:187], 0
	v_mfma_f32_16x16x32_bf16 v[126:129], v[134:137], v[162:165], v[126:129]
	v_mfma_f32_16x16x32_bf16 v[122:125], v[142:145], v[162:165], v[122:125]
	v_mfma_f32_16x16x32_bf16 v[110:113], v[134:137], v[172:175], v[110:113]
	v_mfma_f32_16x16x32_bf16 v[106:109], v[142:145], v[172:175], v[106:109]
	v_mfma_f32_16x16x32_bf16 v[94:97], v[134:137], v[180:183], v[94:97]
	v_mfma_f32_16x16x32_bf16 v[90:93], v[142:145], v[180:183], v[90:93]
	v_mfma_f32_16x16x32_bf16 v[78:81], v[134:137], v[190:193], v[78:81]
	v_mfma_f32_16x16x32_bf16 v[74:77], v[142:145], v[190:193], v[74:77]
	s_barrier
	s_add_i32 m0, s38, 0x10000
	ds_read_b128 v[194:197], v189 offset:16384
	ds_read_b128 v[198:201], v189 offset:17408
	ds_read_b128 v[202:205], v189 offset:18432
	global_load_lds_dwordx4 v148, s[90:91]
	s_add_i32 m0, s38, 0x12000
	ds_read_b128 v[206:209], v189 offset:19456
	global_load_lds_dwordx4 v152, s[90:91]
	s_barrier
	s_waitcnt lgkmcnt(0)
	v_mfma_f32_16x16x32_bf16 v[118:121], v[194:197], v[158:161], 0
	v_mfma_f32_16x16x32_bf16 v[114:117], v[202:205], v[158:161], 0
	v_mfma_f32_16x16x32_bf16 v[102:105], v[194:197], v[166:169], 0
	v_mfma_f32_16x16x32_bf16 v[98:101], v[202:205], v[166:169], 0
	v_mfma_f32_16x16x32_bf16 v[86:89], v[194:197], v[176:179], 0
	v_mfma_f32_16x16x32_bf16 v[82:85], v[202:205], v[176:179], 0
	v_mfma_f32_16x16x32_bf16 v[70:73], v[194:197], v[184:187], 0
	v_mfma_f32_16x16x32_bf16 v[66:69], v[202:205], v[184:187], 0
	v_mfma_f32_16x16x32_bf16 v[118:121], v[198:201], v[162:165], v[118:121]
	v_mfma_f32_16x16x32_bf16 v[114:117], v[206:209], v[162:165], v[114:117]
	v_mfma_f32_16x16x32_bf16 v[102:105], v[198:201], v[172:175], v[102:105]
	v_mfma_f32_16x16x32_bf16 v[98:101], v[206:209], v[172:175], v[98:101]
	v_mfma_f32_16x16x32_bf16 v[86:89], v[198:201], v[180:183], v[86:89]
	v_mfma_f32_16x16x32_bf16 v[82:85], v[206:209], v[180:183], v[82:85]
	v_mfma_f32_16x16x32_bf16 v[70:73], v[198:201], v[190:193], v[70:73]
	v_mfma_f32_16x16x32_bf16 v[66:69], v[206:209], v[190:193], v[66:69]
	s_mov_b32 m0, s39
	s_mov_b64 s[100:101], s[92:93]
	s_barrier
	ds_read_b128 v[158:161], v171 offset:16384
	ds_read_b128 v[162:165], v171 offset:17408
	ds_read_b128 v[166:169], v171 offset:18432
	ds_read_b128 v[172:175], v171 offset:19456
	ds_read_b128 v[176:179], v171 offset:20480
	ds_read_b128 v[180:183], v171 offset:21504
	ds_read_b128 v[184:187], v171 offset:22528
	global_load_lds_dwordx4 v146, s[100:101]
	s_mov_b32 m0, s42
	ds_read_b128 v[190:193], v171 offset:23552
	global_load_lds_dwordx4 v150, s[100:101]
	s_waitcnt vmcnt(10)
	s_barrier
	s_waitcnt lgkmcnt(0)
	v_mfma_f32_16x16x32_bf16 v[62:65], v[130:133], v[158:161], 0
	v_mfma_f32_16x16x32_bf16 v[58:61], v[138:141], v[158:161], 0
	v_mfma_f32_16x16x32_bf16 v[46:49], v[130:133], v[166:169], 0
	v_mfma_f32_16x16x32_bf16 v[42:45], v[138:141], v[166:169], 0
	v_mfma_f32_16x16x32_bf16 v[30:33], v[130:133], v[176:179], 0
	v_mfma_f32_16x16x32_bf16 v[26:29], v[138:141], v[176:179], 0
	v_mfma_f32_16x16x32_bf16 v[14:17], v[130:133], v[184:187], 0
	v_mfma_f32_16x16x32_bf16 v[10:13], v[138:141], v[184:187], 0
	v_mfma_f32_16x16x32_bf16 v[62:65], v[134:137], v[162:165], v[62:65]
	v_mfma_f32_16x16x32_bf16 v[58:61], v[142:145], v[162:165], v[58:61]
	v_mfma_f32_16x16x32_bf16 v[46:49], v[134:137], v[172:175], v[46:49]
	v_mfma_f32_16x16x32_bf16 v[42:45], v[142:145], v[172:175], v[42:45]
	v_mfma_f32_16x16x32_bf16 v[30:33], v[134:137], v[180:183], v[30:33]
	v_mfma_f32_16x16x32_bf16 v[26:29], v[142:145], v[180:183], v[26:29]
	v_mfma_f32_16x16x32_bf16 v[14:17], v[134:137], v[190:193], v[14:17]
	v_mfma_f32_16x16x32_bf16 v[10:13], v[142:145], v[190:193], v[10:13]
	s_barrier
	s_add_u32 s94, s90, 0x40000
	s_addc_u32 s95, s91, 0
	s_add_i32 m0, s38, 0x14000
	s_nop 0
	global_load_lds_dwordx4 v148, s[94:95]
	s_add_i32 m0, s38, 0x16000
	s_nop 0
	global_load_lds_dwordx4 v152, s[94:95]
	ds_read_b128 v[130:133], v189 offset:32768
	ds_read_b128 v[134:137], v189 offset:33792
	ds_read_b128 v[138:141], v189 offset:34816
	ds_read_b128 v[142:145], v189 offset:35840
	s_waitcnt vmcnt(6)
	s_barrier
	v_mfma_f32_16x16x32_bf16 v[54:57], v[194:197], v[158:161], 0
	v_mfma_f32_16x16x32_bf16 v[50:53], v[202:205], v[158:161], 0
	v_mfma_f32_16x16x32_bf16 v[38:41], v[194:197], v[166:169], 0
	v_mfma_f32_16x16x32_bf16 v[34:37], v[202:205], v[166:169], 0
	v_mfma_f32_16x16x32_bf16 v[22:25], v[194:197], v[176:179], 0
	v_mfma_f32_16x16x32_bf16 v[18:21], v[202:205], v[176:179], 0
	v_mfma_f32_16x16x32_bf16 v[6:9], v[194:197], v[184:187], 0
	v_mfma_f32_16x16x32_bf16 v[2:5], v[202:205], v[184:187], 0
	v_mfma_f32_16x16x32_bf16 v[54:57], v[198:201], v[162:165], v[54:57]
	v_mfma_f32_16x16x32_bf16 v[50:53], v[206:209], v[162:165], v[50:53]
	v_mfma_f32_16x16x32_bf16 v[38:41], v[198:201], v[172:175], v[38:41]
	v_mfma_f32_16x16x32_bf16 v[34:37], v[206:209], v[172:175], v[34:37]
	v_mfma_f32_16x16x32_bf16 v[22:25], v[198:201], v[180:183], v[22:25]
	v_mfma_f32_16x16x32_bf16 v[18:21], v[206:209], v[180:183], v[18:21]
	v_mfma_f32_16x16x32_bf16 v[6:9], v[198:201], v[190:193], v[6:9]
	v_mfma_f32_16x16x32_bf16 v[2:5], v[206:209], v[190:193], v[2:5]
	s_barrier
	s_add_u32 s92, s92, 0x40000
	s_addc_u32 s93, s93, 0
	s_mov_b32 m0, s43
	ds_read_b128 v[158:161], v171 offset:32768
	ds_read_b128 v[162:165], v171 offset:33792
	ds_read_b128 v[166:169], v171 offset:34816
	ds_read_b128 v[172:175], v171 offset:35840
	ds_read_b128 v[176:179], v171 offset:36864
	ds_read_b128 v[180:183], v171 offset:37888
	ds_read_b128 v[184:187], v171 offset:38912
	global_load_lds_dwordx4 v146, s[92:93]
	s_mov_b32 m0, s44
	ds_read_b128 v[190:193], v171 offset:39936
	global_load_lds_dwordx4 v150, s[92:93]
	s_waitcnt lgkmcnt(8)
	s_barrier
	s_waitcnt lgkmcnt(0)
	v_mfma_f32_16x16x32_bf16 v[126:129], v[130:133], v[158:161], v[126:129]
	v_mfma_f32_16x16x32_bf16 v[122:125], v[138:141], v[158:161], v[122:125]
	v_mfma_f32_16x16x32_bf16 v[110:113], v[130:133], v[166:169], v[110:113]
	v_mfma_f32_16x16x32_bf16 v[106:109], v[138:141], v[166:169], v[106:109]
	v_mfma_f32_16x16x32_bf16 v[94:97], v[130:133], v[176:179], v[94:97]
	v_mfma_f32_16x16x32_bf16 v[90:93], v[138:141], v[176:179], v[90:93]
	v_mfma_f32_16x16x32_bf16 v[78:81], v[130:133], v[184:187], v[78:81]
	v_mfma_f32_16x16x32_bf16 v[74:77], v[138:141], v[184:187], v[74:77]
	v_mfma_f32_16x16x32_bf16 v[126:129], v[134:137], v[162:165], v[126:129]
	v_mfma_f32_16x16x32_bf16 v[122:125], v[142:145], v[162:165], v[122:125]
	v_mfma_f32_16x16x32_bf16 v[110:113], v[134:137], v[172:175], v[110:113]
	v_mfma_f32_16x16x32_bf16 v[106:109], v[142:145], v[172:175], v[106:109]
	v_mfma_f32_16x16x32_bf16 v[94:97], v[134:137], v[180:183], v[94:97]
	v_mfma_f32_16x16x32_bf16 v[90:93], v[142:145], v[180:183], v[90:93]
	v_mfma_f32_16x16x32_bf16 v[78:81], v[134:137], v[190:193], v[78:81]
	v_mfma_f32_16x16x32_bf16 v[74:77], v[142:145], v[190:193], v[74:77]
	s_barrier
	s_add_i32 m0, s38, 0x18000
	ds_read_b128 v[194:197], v189 offset:49152
	ds_read_b128 v[198:201], v189 offset:50176
	ds_read_b128 v[202:205], v189 offset:51200
	ds_read_b128 v[206:209], v189 offset:52224
	s_add_u32 s98, s90, s40
	s_addc_u32 s99, s91, s41
	global_load_lds_dwordx4 v148, s[98:99]
	s_add_i32 m0, s38, 0x1a000
	s_nop 0
	global_load_lds_dwordx4 v152, s[98:99]
	s_barrier
	s_waitcnt lgkmcnt(0)
	v_mfma_f32_16x16x32_bf16 v[118:121], v[194:197], v[158:161], v[118:121]
	v_mfma_f32_16x16x32_bf16 v[114:117], v[202:205], v[158:161], v[114:117]
	v_mfma_f32_16x16x32_bf16 v[102:105], v[194:197], v[166:169], v[102:105]
	v_mfma_f32_16x16x32_bf16 v[98:101], v[202:205], v[166:169], v[98:101]
	v_mfma_f32_16x16x32_bf16 v[86:89], v[194:197], v[176:179], v[86:89]
	v_mfma_f32_16x16x32_bf16 v[82:85], v[202:205], v[176:179], v[82:85]
	v_mfma_f32_16x16x32_bf16 v[70:73], v[194:197], v[184:187], v[70:73]
	v_mfma_f32_16x16x32_bf16 v[66:69], v[202:205], v[184:187], v[66:69]
	v_mfma_f32_16x16x32_bf16 v[118:121], v[198:201], v[162:165], v[118:121]
	v_mfma_f32_16x16x32_bf16 v[114:117], v[206:209], v[162:165], v[114:117]
	v_mfma_f32_16x16x32_bf16 v[102:105], v[198:201], v[172:175], v[102:105]
	v_mfma_f32_16x16x32_bf16 v[98:101], v[206:209], v[172:175], v[98:101]
	v_mfma_f32_16x16x32_bf16 v[86:89], v[198:201], v[180:183], v[86:89]
	v_mfma_f32_16x16x32_bf16 v[82:85], v[206:209], v[180:183], v[82:85]
	v_mfma_f32_16x16x32_bf16 v[70:73], v[198:201], v[190:193], v[70:73]
	v_mfma_f32_16x16x32_bf16 v[66:69], v[206:209], v[190:193], v[66:69]
	s_mov_b32 m0, s60
	s_barrier
	ds_read_b128 v[158:161], v171 offset:49152
	ds_read_b128 v[162:165], v171 offset:50176
	ds_read_b128 v[166:169], v171 offset:51200
	ds_read_b128 v[172:175], v171 offset:52224
	ds_read_b128 v[176:179], v171 offset:53248
	ds_read_b128 v[180:183], v171 offset:54272
	ds_read_b128 v[184:187], v171 offset:55296
	ds_read_b128 v[190:193], v171 offset:56320
	s_add_u32 s98, s100, s40
	s_addc_u32 s99, s101, s41
	global_load_lds_dwordx4 v146, s[98:99]
	s_mov_b32 m0, s61
	s_nop 0
	global_load_lds_dwordx4 v150, s[98:99]
	s_waitcnt vmcnt(10)
	s_barrier
	s_waitcnt lgkmcnt(0)
	v_mfma_f32_16x16x32_bf16 v[62:65], v[130:133], v[158:161], v[62:65]
	v_mfma_f32_16x16x32_bf16 v[58:61], v[138:141], v[158:161], v[58:61]
	v_mfma_f32_16x16x32_bf16 v[46:49], v[130:133], v[166:169], v[46:49]
	v_mfma_f32_16x16x32_bf16 v[42:45], v[138:141], v[166:169], v[42:45]
	v_mfma_f32_16x16x32_bf16 v[30:33], v[130:133], v[176:179], v[30:33]
	v_mfma_f32_16x16x32_bf16 v[26:29], v[138:141], v[176:179], v[26:29]
	v_mfma_f32_16x16x32_bf16 v[14:17], v[130:133], v[184:187], v[14:17]
	v_mfma_f32_16x16x32_bf16 v[10:13], v[138:141], v[184:187], v[10:13]
	v_mfma_f32_16x16x32_bf16 v[62:65], v[134:137], v[162:165], v[62:65]
	v_mfma_f32_16x16x32_bf16 v[58:61], v[142:145], v[162:165], v[58:61]
	v_mfma_f32_16x16x32_bf16 v[46:49], v[134:137], v[172:175], v[46:49]
	v_mfma_f32_16x16x32_bf16 v[42:45], v[142:145], v[172:175], v[42:45]
	v_mfma_f32_16x16x32_bf16 v[30:33], v[134:137], v[180:183], v[30:33]
	v_mfma_f32_16x16x32_bf16 v[26:29], v[142:145], v[180:183], v[26:29]
	v_mfma_f32_16x16x32_bf16 v[14:17], v[134:137], v[190:193], v[14:17]
	v_mfma_f32_16x16x32_bf16 v[10:13], v[142:145], v[190:193], v[10:13]
	s_barrier
	s_add_u32 s90, s90, 0x40080
	s_addc_u32 s91, s91, 0
	s_add_i32 m0, s38, 0x1c000
	s_nop 0
	global_load_lds_dwordx4 v148, s[90:91]
	s_add_i32 m0, s38, 0x1e000
	s_nop 0
	global_load_lds_dwordx4 v152, s[90:91]
	ds_read_b128 v[130:133], v189
	ds_read_b128 v[134:137], v189 offset:1024
	ds_read_b128 v[138:141], v189 offset:2048
	ds_read_b128 v[142:145], v189 offset:3072
	s_waitcnt vmcnt(6)
	s_barrier
	v_mfma_f32_16x16x32_bf16 v[54:57], v[194:197], v[158:161], v[54:57]
	v_mfma_f32_16x16x32_bf16 v[50:53], v[202:205], v[158:161], v[50:53]
	v_mfma_f32_16x16x32_bf16 v[38:41], v[194:197], v[166:169], v[38:41]
	v_mfma_f32_16x16x32_bf16 v[34:37], v[202:205], v[166:169], v[34:37]
	v_mfma_f32_16x16x32_bf16 v[22:25], v[194:197], v[176:179], v[22:25]
	v_mfma_f32_16x16x32_bf16 v[18:21], v[202:205], v[176:179], v[18:21]
	v_mfma_f32_16x16x32_bf16 v[6:9], v[194:197], v[184:187], v[6:9]
	v_mfma_f32_16x16x32_bf16 v[2:5], v[202:205], v[184:187], v[2:5]
	v_mfma_f32_16x16x32_bf16 v[54:57], v[198:201], v[162:165], v[54:57]
	v_mfma_f32_16x16x32_bf16 v[50:53], v[206:209], v[162:165], v[50:53]
	v_mfma_f32_16x16x32_bf16 v[38:41], v[198:201], v[172:175], v[38:41]
	v_mfma_f32_16x16x32_bf16 v[34:37], v[206:209], v[172:175], v[34:37]
	v_mfma_f32_16x16x32_bf16 v[22:25], v[198:201], v[180:183], v[22:25]
	v_mfma_f32_16x16x32_bf16 v[18:21], v[206:209], v[180:183], v[18:21]
	v_mfma_f32_16x16x32_bf16 v[6:9], v[198:201], v[190:193], v[6:9]
	v_mfma_f32_16x16x32_bf16 v[2:5], v[206:209], v[190:193], v[2:5]
	s_add_i32 s85, s85, 2
	s_add_u32 s88, s88, 0x100
	s_addc_u32 s89, s89, 0
	s_add_u32 s34, s34, 0x100
	s_addc_u32 s79, s79, 0
	s_add_u32 s87, s88, 0xfffc0080
	s_addc_u32 s90, s89, -1
	s_cmp_eq_u32 s85, 12
	s_cselect_b32 s93, s13, s90
	s_cselect_b32 s92, s22, s87
	s_cselect_b32 s91, s7, s79
	s_cselect_b32 s90, s23, s34
	s_cmp_gt_u32 s85, 13
	s_barrier
	.p2align 6
	s_nop 0
	s_nop 0
	s_nop 0
	s_nop 0
	s_nop 0
	s_nop 0
	s_nop 0
	s_nop 0
